# EpiResid epilogues of P10/P15/P18: all 16 residual loads issued up front (counted vmcnt), instead of 4 serialized rounds
# speedup vs baseline: 1.0002x; 1.0002x over previous
;     __device__ __forceinline__ void operator()(const f32x4 (&acc)[2][2][4][2], const Unit& u, int wr, int wc, int fr, int fq) const {
;     ...
; #pragma unroll
;             for (int m2 = 0; m2 < 2; ++m2)
; #pragma unroll
;                 for (int bj = 0; bj < 2; ++bj) {
;                     const size_t off = (size_t)(u.pm * BM + ai * HALF + wr * 64 + (2 * mh + m2) * 16 + fr) * 1024 + col0 + bj * HALF;
;                     if (!basef) bh[m2][bj] = *(const u32x4*)(xin + off);
;                 }
; #pragma unroll
;             for (int m2 = 0; m2 < 2; ++m2) {
;                 const int m = 2 * mh + m2;
;                 const int row = u.pm * BM + ai * HALF + wr * 64 + m * 16 + fr; float sq = 0.f;
;                 if (basef) {
; #pragma unroll
;                     for (int bj = 0; bj < 2; ++bj) { const size_t off = (size_t)row * 1024 + col0 + bj * HALF; bf[m2][bj][0] = *(const f32x4*)(basef + off); bf[m2][bj][1] = *(const f32x4*)(basef + off + 4); }
;                 }
; #pragma unroll
;                 for (int bj = 0; bj < 2; ++bj) {
;                     const size_t off = (size_t)row * 1024 + col0 + bj * HALF;
;                     float bv[8];
;                     if (basef) { const f32x4 b0 = bf[m2][bj][0], b1 = bf[m2][bj][1]; bv[0] = b0[0]; bv[1] = b0[1]; bv[2] = b0[2]; bv[3] = b0[3]; bv[4] = b1[0]; bv[5] = b1[1]; bv[6] = b1[2]; bv[7] = b1[3]; }
;                     else { const u32x4 gw = bh[m2][bj];
;                         bv[0] = __uint_as_float(gw.x << 16); bv[1] = __uint_as_float(gw.x & 0xffff0000u); bv[2] = __uint_as_float(gw.y << 16); bv[3] = __uint_as_float(gw.y & 0xffff0000u);
;                         bv[4] = __uint_as_float(gw.z << 16); bv[5] = __uint_as_float(gw.z & 0xffff0000u); bv[6] = __uint_as_float(gw.w << 16); bv[7] = __uint_as_float(gw.w & 0xffff0000u); }
;                     float y[8];
; #pragma unroll
;                     for (int e = 0; e < 4; ++e) { y[e] = bv[e] + alpha * acc[ai][bj][m][0][e]; y[4 + e] = bv[4 + e] + alpha * acc[ai][bj][m][1][e]; }
;                     u32x4 w; w.x = cvt_pk_bf16(y[0], y[1]); w.y = cvt_pk_bf16(y[2], y[3]); w.z = cvt_pk_bf16(y[4], y[5]); w.w = cvt_pk_bf16(y[6], y[7]);
;                     *(u32x4*)(xs + off) = w;
;                     if (ss) sq += ((y[0] * y[0] + y[1] * y[1]) + (y[2] * y[2] + y[3] * y[3])) + ((y[4] * y[4] + y[5] * y[5]) + (y[6] * y[6] + y[7] * y[7]));
;                 }
.LBB0_2893:
	v_lshl_or_b32 v152, s47, 8, v164
	v_lshl_add_u32 v154, s2, 8, v162
	v_ashrrev_i32_e32 v153, 31, v152
	v_lshlrev_b64 v[178:179], 1, v[152:153]
	v_ashrrev_i32_e32 v155, 31, v154
	v_lshl_add_u64 v[156:157], s[90:91], 0, v[178:179]
	v_lshlrev_b64 v[180:181], 11, v[154:155]
	v_lshl_add_u64 v[128:129], v[156:157], 0, v[180:181]
	v_lshl_add_u64 v[248:249], v[156:157], 0, v[180:181]
	global_load_dwordx4 v[170:173], v[128:129], off
	global_load_dwordx4 v[174:177], v[128:129], off offset:256
	v_or_b32_e32 v158, 16, v154
	v_ashrrev_i32_e32 v159, 31, v158
	v_lshlrev_b64 v[160:161], 11, v[158:159]
	v_lshl_add_u64 v[128:129], v[156:157], 0, v[160:161]
	global_load_dwordx4 v[132:135], v[128:129], off
	s_nop 0
	global_load_dwordx4 v[128:131], v[128:129], off offset:256
	s_mov_b32 s99, 0
	s_mov_b32 s98, 0x10000
	v_lshl_add_u64 v[250:251], v[248:249], 0, s[98:99]
	global_load_dwordx4 v[190:193], v[250:251], off
	global_load_dwordx4 v[194:197], v[250:251], off offset:256
	s_mov_b32 s98, 0x8000
	v_lshl_add_u64 v[248:249], v[250:251], 0, s[98:99]
	global_load_dwordx4 v[200:203], v[248:249], off
	global_load_dwordx4 v[204:207], v[248:249], off offset:256
	s_mov_b32 s98, 0x28000
	v_lshl_add_u64 v[250:251], v[248:249], 0, s[98:99]
	global_load_dwordx4 v[208:211], v[250:251], off
	global_load_dwordx4 v[212:215], v[250:251], off offset:256
	s_mov_b32 s98, 0x8000
	v_lshl_add_u64 v[248:249], v[250:251], 0, s[98:99]
	global_load_dwordx4 v[216:219], v[248:249], off
	global_load_dwordx4 v[228:231], v[248:249], off offset:256
	s_mov_b32 s98, 0x8000
	v_lshl_add_u64 v[250:251], v[248:249], 0, s[98:99]
	global_load_dwordx4 v[232:235], v[250:251], off
	global_load_dwordx4 v[236:239], v[250:251], off offset:256
	s_mov_b32 s98, 0x8000
	v_lshl_add_u64 v[248:249], v[250:251], 0, s[98:99]
	global_load_dwordx4 v[240:243], v[248:249], off
	global_load_dwordx4 v[244:247], v[248:249], off offset:256
	v_and_b32_e32 v182, 64, v168
	v_xor_b32_e32 v169, 16, v168
	v_add_u32_e32 v182, 64, v182
	v_xor_b32_e32 v183, 32, v168
	v_cmp_lt_i32_e32 vcc, v169, v182
	v_lshl_add_u64 v[180:181], s[92:93], 0, v[180:181]
	v_lshl_add_u64 v[178:179], v[180:181], 0, v[178:179]
	v_cndmask_b32_e32 v169, v168, v169, vcc
	v_cmp_lt_i32_e32 vcc, v183, v182
	v_lshlrev_b32_e32 v169, 2, v169
	s_lshl_b32 s26, s47, 2
	v_cndmask_b32_e32 v182, v168, v183, vcc
	s_ashr_i32 s27, s26, 31
	s_waitcnt vmcnt(12)
	v_lshlrev_b32_e32 v180, 16, v170
	v_and_b32_e32 v170, 0xffff0000, v170
	v_lshlrev_b32_e32 v181, 16, v171
	v_and_b32_e32 v171, 0xffff0000, v171
	v_lshlrev_b32_e32 v183, 16, v172
	v_and_b32_e32 v172, 0xffff0000, v172
	v_lshlrev_b32_e32 v184, 16, v173
	v_and_b32_e32 v173, 0xffff0000, v173
	v_lshlrev_b32_e32 v185, 16, v174
	v_and_b32_e32 v174, 0xffff0000, v174
	v_lshlrev_b32_e32 v186, 16, v175
	v_and_b32_e32 v175, 0xffff0000, v175
	v_lshlrev_b32_e32 v187, 16, v176
	v_and_b32_e32 v176, 0xffff0000, v176
	v_lshlrev_b32_e32 v188, 16, v177
	v_and_b32_e32 v177, 0xffff0000, v177
	v_add_f32_e32 v125, v125, v170
	v_add_f32_e32 v121, v121, v172
	v_add_f32_e32 v127, v127, v171
	v_add_f32_e32 v123, v123, v173
	v_add_f32_e32 v117, v117, v174
	v_add_f32_e32 v171, v113, v176
	v_add_f32_e32 v119, v119, v175
	v_add_f32_e32 v173, v115, v177
	v_add_f32_e32 v124, v124, v180
	v_add_f32_e32 v120, v120, v183
	v_add_f32_e32 v126, v126, v181
	v_add_f32_e32 v122, v122, v184
	v_add_f32_e32 v116, v116, v185
	v_add_f32_e32 v170, v112, v187
	v_add_f32_e32 v118, v118, v186
	v_add_f32_e32 v172, v114, v188
	v_cvt_pk_bf16_f32 v112, v124, v125
	v_cvt_pk_bf16_f32 v113, v126, v127
	v_mul_f32_e32 v114, v125, v125
	v_mul_f32_e32 v115, v127, v127
	v_mul_f32_e32 v125, v121, v121
	v_mul_f32_e32 v127, v123, v123
	v_mul_f32_e32 v174, v117, v117
	v_mul_f32_e32 v175, v119, v119
	v_mul_f32_e32 v176, v171, v171
	v_mul_f32_e32 v177, v173, v173
	v_fmac_f32_e32 v114, v124, v124
	v_fmac_f32_e32 v115, v126, v126
	v_fmac_f32_e32 v125, v120, v120
	v_fmac_f32_e32 v127, v122, v122
	v_fmac_f32_e32 v174, v116, v116
	v_fmac_f32_e32 v175, v118, v118
	v_fmac_f32_e32 v176, v170, v170
	v_fmac_f32_e32 v177, v172, v172
	v_add_f32_e32 v114, v114, v115
	v_add_f32_e32 v115, v125, v127
	v_add_f32_e32 v124, v174, v175
	v_add_f32_e32 v125, v176, v177
	v_add_f32_e32 v114, v114, v115
	v_add_f32_e32 v115, v124, v125
	v_add_f32_e32 v124, v114, v115
	ds_bpermute_b32 v125, v169, v124
	v_cvt_pk_bf16_f32 v114, v120, v121
	v_cvt_pk_bf16_f32 v115, v122, v123
	global_store_dwordx4 v[178:179], v[112:115], off
	v_cvt_pk_bf16_f32 v116, v116, v117
	v_cvt_pk_bf16_f32 v117, v118, v119
	v_cvt_pk_bf16_f32 v118, v170, v171
	v_cvt_pk_bf16_f32 v119, v172, v173
	global_store_dwordx4 v[178:179], v[116:119], off offset:256
	s_waitcnt lgkmcnt(0)
	v_add_f32_e32 v113, v124, v125
	v_lshlrev_b32_e32 v112, 2, v182
	ds_bpermute_b32 v114, v112, v113
	s_and_saveexec_b64 s[28:29], s[8:9]
	s_cbranch_execz .LBB0_2895
	s_waitcnt lgkmcnt(0)
	v_add_f32_e32 v113, v113, v114
	v_lshlrev_b64 v[114:115], 6, v[154:155]
	v_lshl_add_u64 v[114:115], s[0:1], 0, v[114:115]
	v_lshl_add_u64 v[114:115], s[26:27], 2, v[114:115]
	s_lshl_b32 s2, s38, 2
	v_lshl_add_u64 v[114:115], v[114:115], 0, s[2:3]
	global_store_dword v[114:115], v113, off

; __device__ __forceinline__ unsigned cvt_pk_bf16(float lo, float hi) { unsigned r; asm volatile("v_cvt_pk_bf16_f32 %0, %1, %2" : "=v"(r) : "v"(lo), "v"(hi)); return r; }
;     __device__ __forceinline__ void operator()(const f32x4 (&acc)[2][2][4][2], const Unit& u, int wr, int wc, int fr, int fq) const {
;     ...
; #pragma unroll
;             for (int m2 = 0; m2 < 2; ++m2) {
;                 const int m = 2 * mh + m2;
;                 const int row = u.pm * BM + ai * HALF + wr * 64 + m * 16 + fr; float sq = 0.f;
;                 if (basef) {
; #pragma unroll
;                     for (int bj = 0; bj < 2; ++bj) { const size_t off = (size_t)row * 1024 + col0 + bj * HALF; bf[m2][bj][0] = *(const f32x4*)(basef + off); bf[m2][bj][1] = *(const f32x4*)(basef + off + 4); }
;                 }
; #pragma unroll
;                 for (int bj = 0; bj < 2; ++bj) {
;                     const size_t off = (size_t)row * 1024 + col0 + bj * HALF;
;                     float bv[8];
;                     if (basef) { const f32x4 b0 = bf[m2][bj][0], b1 = bf[m2][bj][1]; bv[0] = b0[0]; bv[1] = b0[1]; bv[2] = b0[2]; bv[3] = b0[3]; bv[4] = b1[0]; bv[5] = b1[1]; bv[6] = b1[2]; bv[7] = b1[3]; }
;                     else { const u32x4 gw = bh[m2][bj];
;                         bv[0] = __uint_as_float(gw.x << 16); bv[1] = __uint_as_float(gw.x & 0xffff0000u); bv[2] = __uint_as_float(gw.y << 16); bv[3] = __uint_as_float(gw.y & 0xffff0000u);
;                         bv[4] = __uint_as_float(gw.z << 16); bv[5] = __uint_as_float(gw.z & 0xffff0000u); bv[6] = __uint_as_float(gw.w << 16); bv[7] = __uint_as_float(gw.w & 0xffff0000u); }
;                     float y[8];
; #pragma unroll
;                     for (int e = 0; e < 4; ++e) { y[e] = bv[e] + alpha * acc[ai][bj][m][0][e]; y[4 + e] = bv[4 + e] + alpha * acc[ai][bj][m][1][e]; }
;                     u32x4 w; w.x = cvt_pk_bf16(y[0], y[1]); w.y = cvt_pk_bf16(y[2], y[3]); w.z = cvt_pk_bf16(y[4], y[5]); w.w = cvt_pk_bf16(y[6], y[7]);
;                     *(u32x4*)(xs + off) = w;
;                     if (ss) sq += ((y[0] * y[0] + y[1] * y[1]) + (y[2] * y[2] + y[3] * y[3])) + ((y[4] * y[4] + y[5] * y[5]) + (y[6] * y[6] + y[7] * y[7]));
;                 }
;                 if (ss) { sq += __shfl_xor(sq, 16); sq += __shfl_xor(sq, 32); if (fq == 0) ss[(size_t)row * 16 + u.pn * 4 + wc] = sq; }
.LBB0_2897:
	s_or_b64 exec, exec, s[28:29]
	v_or_b32_e32 v108, 32, v154
	v_ashrrev_i32_e32 v109, 31, v108
	v_lshlrev_b64 v[110:111], 11, v[108:109]
	s_waitcnt lgkmcnt(0)
	v_lshl_add_u64 v[96:97], v[156:157], 0, v[110:111]
	v_or_b32_e32 v104, 48, v154
	v_ashrrev_i32_e32 v105, 31, v104
	v_lshlrev_b64 v[106:107], 11, v[104:105]
	v_lshl_add_u64 v[96:97], v[156:157], 0, v[106:107]
	s_nop 0
	s_waitcnt vmcnt(12)
	v_lshlrev_b32_e32 v113, 16, v190
	v_and_b32_e32 v114, 0xffff0000, v190
	v_lshlrev_b32_e32 v122, 16, v191
	v_and_b32_e32 v115, 0xffff0000, v191
	v_lshlrev_b32_e32 v123, 16, v192
	v_and_b32_e32 v116, 0xffff0000, v192
	v_lshlrev_b32_e32 v124, 16, v193
	v_and_b32_e32 v117, 0xffff0000, v193
	s_waitcnt vmcnt(12)
	v_lshlrev_b32_e32 v125, 16, v194
	v_and_b32_e32 v118, 0xffff0000, v194
	v_lshlrev_b32_e32 v126, 16, v195
	v_and_b32_e32 v119, 0xffff0000, v195
	v_lshlrev_b32_e32 v127, 16, v196
	v_and_b32_e32 v120, 0xffff0000, v196
	v_lshlrev_b32_e32 v128, 16, v197
	v_and_b32_e32 v121, 0xffff0000, v197
	v_add_f32_e32 v93, v93, v114
	v_add_f32_e32 v89, v89, v116
	v_add_f32_e32 v95, v95, v115
	v_add_f32_e32 v91, v91, v117
	v_add_f32_e32 v115, v85, v118
	v_add_f32_e32 v116, v81, v120
	v_add_f32_e32 v119, v87, v119
	v_add_f32_e32 v120, v83, v121
	v_add_f32_e32 v92, v92, v113
	v_add_f32_e32 v88, v88, v123
	v_add_f32_e32 v94, v94, v122
	v_add_f32_e32 v90, v90, v124
	v_add_f32_e32 v113, v84, v125
	v_add_f32_e32 v114, v80, v127
	v_add_f32_e32 v117, v86, v126
	v_add_f32_e32 v118, v82, v128
	v_cvt_pk_bf16_f32 v80, v92, v93
	v_cvt_pk_bf16_f32 v81, v94, v95
	v_cvt_pk_bf16_f32 v82, v88, v89
	v_cvt_pk_bf16_f32 v83, v90, v91
	v_mul_f32_e32 v84, v93, v93
	v_mul_f32_e32 v85, v95, v95
	v_mul_f32_e32 v86, v89, v89
	v_mul_f32_e32 v87, v91, v91
	v_mul_f32_e32 v89, v115, v115
	v_mul_f32_e32 v91, v119, v119
	v_mul_f32_e32 v93, v116, v116
	v_mul_f32_e32 v95, v120, v120
	v_fmac_f32_e32 v84, v92, v92
	v_fmac_f32_e32 v85, v94, v94
	v_fmac_f32_e32 v86, v88, v88
	v_fmac_f32_e32 v87, v90, v90
	v_fmac_f32_e32 v89, v113, v113
	v_fmac_f32_e32 v91, v117, v117
	v_fmac_f32_e32 v93, v114, v114
	v_fmac_f32_e32 v95, v118, v118
	v_add_f32_e32 v84, v84, v85
	v_add_f32_e32 v85, v86, v87
	v_add_f32_e32 v86, v89, v91
	v_add_f32_e32 v87, v93, v95
	v_add_f32_e32 v84, v84, v85
	v_add_f32_e32 v85, v86, v87
	v_add_f32_e32 v88, v84, v85
	ds_bpermute_b32 v89, v169, v88
	v_lshl_add_u64 v[84:85], s[92:93], 0, v[110:111]
	v_lshl_add_u64 v[86:87], v[152:153], 1, v[84:85]
	global_store_dwordx4 v[86:87], v[80:83], off
	s_waitcnt lgkmcnt(0)
	s_nop 0
	v_add_f32_e32 v80, v88, v89
	ds_bpermute_b32 v81, v112, v80
	v_cvt_pk_bf16_f32 v82, v113, v115
	v_cvt_pk_bf16_f32 v83, v117, v119
	v_cvt_pk_bf16_f32 v84, v114, v116
	v_cvt_pk_bf16_f32 v85, v118, v120
	global_store_dwordx4 v[86:87], v[82:85], off offset:256
	s_and_saveexec_b64 s[28:29], s[8:9]
	s_cbranch_execz .LBB0_2899
	s_waitcnt lgkmcnt(0)
	v_add_f32_e32 v82, v80, v81
	v_lshlrev_b64 v[80:81], 6, v[108:109]
	v_lshl_add_u64 v[80:81], s[0:1], 0, v[80:81]
	v_lshl_add_u64 v[80:81], s[26:27], 2, v[80:81]
	s_lshl_b32 s2, s38, 2
	v_lshl_add_u64 v[80:81], v[80:81], 0, s[2:3]
	global_store_dword v[80:81], v82, off
.LBB0_2899:
	s_or_b64 exec, exec, s[28:29]
	s_waitcnt vmcnt(12) lgkmcnt(0)
	v_and_b32_e32 v81, 0xffff0000, v200
	v_lshlrev_b32_e32 v80, 16, v200
	v_and_b32_e32 v83, 0xffff0000, v201
	v_lshlrev_b32_e32 v84, 16, v202
	v_add_f32_e32 v77, v77, v81
	v_lshlrev_b32_e32 v82, 16, v201
	v_add_f32_e32 v76, v76, v80
	v_add_f32_e32 v80, v72, v84
	v_add_f32_e32 v79, v79, v83
	v_cvt_pk_bf16_f32 v72, v76, v77
	v_mul_f32_e32 v77, v77, v77
	v_and_b32_e32 v85, 0xffff0000, v202
	v_and_b32_e32 v87, 0xffff0000, v203
	v_add_f32_e32 v78, v78, v82
	v_fmac_f32_e32 v77, v76, v76
	v_mul_f32_e32 v76, v79, v79
	v_lshlrev_b32_e32 v86, 16, v203
	v_add_f32_e32 v81, v73, v85
	v_add_f32_e32 v83, v75, v87
	v_fmac_f32_e32 v76, v78, v78
	v_add_f32_e32 v82, v74, v86
	v_cvt_pk_bf16_f32 v73, v78, v79
	v_add_f32_e32 v76, v77, v76
	v_mul_f32_e32 v77, v81, v81
	v_mul_f32_e32 v78, v83, v83
	v_fmac_f32_e32 v77, v80, v80
	v_fmac_f32_e32 v78, v82, v82
	v_cvt_pk_bf16_f32 v74, v80, v81
	v_add_f32_e32 v77, v77, v78
	s_waitcnt vmcnt(12)
	v_and_b32_e32 v78, 0xffff0000, v204
	v_and_b32_e32 v80, 0xffff0000, v205
	v_cvt_pk_bf16_f32 v75, v82, v83
	v_add_f32_e32 v76, v76, v77
	v_lshlrev_b32_e32 v77, 16, v204
	v_lshlrev_b32_e32 v79, 16, v205
	v_lshlrev_b32_e32 v81, 16, v206
	v_and_b32_e32 v82, 0xffff0000, v206
	v_add_f32_e32 v69, v69, v78
	v_add_f32_e32 v80, v71, v80
	v_and_b32_e32 v84, 0xffff0000, v207
	v_add_f32_e32 v68, v68, v77
	v_add_f32_e32 v77, v64, v81
	v_add_f32_e32 v78, v65, v82
	v_add_f32_e32 v79, v70, v79
	v_mul_f32_e32 v64, v69, v69
	v_mul_f32_e32 v65, v80, v80
	v_lshlrev_b32_e32 v83, 16, v207
	v_add_f32_e32 v82, v67, v84
	v_fmac_f32_e32 v64, v68, v68
	v_fmac_f32_e32 v65, v79, v79
	v_add_f32_e32 v81, v66, v83
	v_add_f32_e32 v64, v64, v65
	v_mul_f32_e32 v65, v78, v78
	v_mul_f32_e32 v66, v82, v82
	v_fmac_f32_e32 v65, v77, v77
	v_fmac_f32_e32 v66, v81, v81
	v_add_f32_e32 v65, v65, v66
	v_add_f32_e32 v64, v64, v65
	v_add_f32_e32 v67, v76, v64
	ds_bpermute_b32 v76, v169, v67
	v_lshl_add_u64 v[64:65], s[92:93], 0, v[106:107]
	v_lshl_add_u64 v[70:71], v[152:153], 1, v[64:65]
	global_store_dwordx4 v[70:71], v[72:75], off
	v_cvt_pk_bf16_f32 v66, v68, v69
	s_waitcnt lgkmcnt(0)
	v_add_f32_e32 v64, v67, v76
	ds_bpermute_b32 v65, v112, v64
	v_cvt_pk_bf16_f32 v67, v79, v80
	v_cvt_pk_bf16_f32 v68, v77, v78
	v_cvt_pk_bf16_f32 v69, v81, v82
	global_store_dwordx4 v[70:71], v[66:69], off offset:256
	s_and_saveexec_b64 s[28:29], s[8:9]
	s_cbranch_execz .LBB0_2901
	s_waitcnt lgkmcnt(0)
	v_add_f32_e32 v66, v64, v65
	v_lshlrev_b64 v[64:65], 6, v[104:105]
	v_lshl_add_u64 v[64:65], s[0:1], 0, v[64:65]
	v_lshl_add_u64 v[64:65], s[26:27], 2, v[64:65]
	s_lshl_b32 s2, s38, 2
	v_lshl_add_u64 v[64:65], v[64:65], 0, s[2:3]
	global_store_dword v[64:65], v66, off
;     __device__ __forceinline__ void operator()(const f32x4 (&acc)[2][2][4][2], const Unit& u, int wr, int wc, int fr, int fq) const {
;     ...
;                     const size_t off = (size_t)(u.pm * BM + ai * HALF + wr * 64 + (2 * mh + m2) * 16 + fr) * 1024 + col0 + bj * HALF;
;                     if (!basef) bh[m2][bj] = *(const u32x4*)(xin + off);
;                 }
; #pragma unroll
;             for (int m2 = 0; m2 < 2; ++m2) {
;                 const int m = 2 * mh + m2;
;                 const int row = u.pm * BM + ai * HALF + wr * 64 + m * 16 + fr; float sq = 0.f;
;                 if (basef) {
; #pragma unroll
;                     for (int bj = 0; bj < 2; ++bj) { const size_t off = (size_t)row * 1024 + col0 + bj * HALF; bf[m2][bj][0] = *(const f32x4*)(basef + off); bf[m2][bj][1] = *(const f32x4*)(basef + off + 4); }
;                 }
; #pragma unroll
;                 for (int bj = 0; bj < 2; ++bj) {
;                     const size_t off = (size_t)row * 1024 + col0 + bj * HALF;
;                     float bv[8];
;                     if (basef) { const f32x4 b0 = bf[m2][bj][0], b1 = bf[m2][bj][1]; bv[0] = b0[0]; bv[1] = b0[1]; bv[2] = b0[2]; bv[3] = b0[3]; bv[4] = b1[0]; bv[5] = b1[1]; bv[6] = b1[2]; bv[7] = b1[3]; }
;                     else { const u32x4 gw = bh[m2][bj];
;                         bv[0] = __uint_as_float(gw.x << 16); bv[1] = __uint_as_float(gw.x & 0xffff0000u); bv[2] = __uint_as_float(gw.y << 16); bv[3] = __uint_as_float(gw.y & 0xffff0000u);
;                         bv[4] = __uint_as_float(gw.z << 16); bv[5] = __uint_as_float(gw.z & 0xffff0000u); bv[6] = __uint_as_float(gw.w << 16); bv[7] = __uint_as_float(gw.w & 0xffff0000u); }
;                     float y[8];
; #pragma unroll
;                     for (int e = 0; e < 4; ++e) { y[e] = bv[e] + alpha * acc[ai][bj][m][0][e]; y[4 + e] = bv[4 + e] + alpha * acc[ai][bj][m][1][e]; }
;                     u32x4 w; w.x = cvt_pk_bf16(y[0], y[1]); w.y = cvt_pk_bf16(y[2], y[3]); w.z = cvt_pk_bf16(y[4], y[5]); w.w = cvt_pk_bf16(y[6], y[7]);
;                     *(u32x4*)(xs + off) = w;
;                     if (ss) sq += ((y[0] * y[0] + y[1] * y[1]) + (y[2] * y[2] + y[3] * y[3])) + ((y[4] * y[4] + y[5] * y[5]) + (y[6] * y[6] + y[7] * y[7]));
;                 }
.LBB0_2901:
	s_or_b64 exec, exec, s[28:29]
	v_add_u32_e32 v76, 0x80, v154
	v_ashrrev_i32_e32 v77, 31, v76
	v_lshlrev_b64 v[86:87], 11, v[76:77]
	s_waitcnt lgkmcnt(0)
	v_lshl_add_u64 v[64:65], v[156:157], 0, v[86:87]
	v_add_u32_e32 v72, 0x90, v154
	v_ashrrev_i32_e32 v73, 31, v72
	v_lshlrev_b64 v[74:75], 11, v[72:73]
	v_lshl_add_u64 v[64:65], v[156:157], 0, v[74:75]
	s_nop 0
	s_waitcnt vmcnt(12)
	v_lshlrev_b32_e32 v88, 16, v208
	v_and_b32_e32 v78, 0xffff0000, v208
	v_lshlrev_b32_e32 v89, 16, v209
	v_and_b32_e32 v79, 0xffff0000, v209
	v_lshlrev_b32_e32 v90, 16, v210
	v_and_b32_e32 v80, 0xffff0000, v210
	v_lshlrev_b32_e32 v91, 16, v211
	v_and_b32_e32 v81, 0xffff0000, v211
	s_waitcnt vmcnt(12)
	v_lshlrev_b32_e32 v92, 16, v212
	v_and_b32_e32 v82, 0xffff0000, v212
	v_lshlrev_b32_e32 v93, 16, v213
	v_and_b32_e32 v83, 0xffff0000, v213
	v_lshlrev_b32_e32 v94, 16, v214
	v_and_b32_e32 v84, 0xffff0000, v214
	v_lshlrev_b32_e32 v95, 16, v215
	v_and_b32_e32 v85, 0xffff0000, v215
	v_add_f32_e32 v61, v61, v78
	v_add_f32_e32 v57, v57, v80
	v_add_f32_e32 v63, v63, v79
	v_add_f32_e32 v59, v59, v81
	v_add_f32_e32 v80, v53, v82
	v_add_f32_e32 v81, v49, v84
	v_add_f32_e32 v83, v55, v83
	v_add_f32_e32 v85, v51, v85
	v_add_f32_e32 v60, v60, v88
	v_add_f32_e32 v56, v56, v90
	v_add_f32_e32 v62, v62, v89
	v_add_f32_e32 v58, v58, v91
	v_add_f32_e32 v78, v52, v92
	v_add_f32_e32 v79, v48, v94
	v_add_f32_e32 v82, v54, v93
	v_add_f32_e32 v84, v50, v95
	v_cvt_pk_bf16_f32 v48, v60, v61
	v_cvt_pk_bf16_f32 v49, v62, v63
	v_cvt_pk_bf16_f32 v50, v56, v57
	v_cvt_pk_bf16_f32 v51, v58, v59
	v_mul_f32_e32 v52, v61, v61
	v_mul_f32_e32 v53, v63, v63
	v_mul_f32_e32 v54, v57, v57
	v_mul_f32_e32 v55, v59, v59
	v_mul_f32_e32 v57, v80, v80
	v_mul_f32_e32 v59, v83, v83
	v_mul_f32_e32 v61, v81, v81
	v_mul_f32_e32 v63, v85, v85
	v_fmac_f32_e32 v52, v60, v60
	v_fmac_f32_e32 v53, v62, v62
	v_fmac_f32_e32 v54, v56, v56
	v_fmac_f32_e32 v55, v58, v58
	v_fmac_f32_e32 v57, v78, v78
	v_fmac_f32_e32 v59, v82, v82
	v_fmac_f32_e32 v61, v79, v79
	v_fmac_f32_e32 v63, v84, v84
	v_add_f32_e32 v52, v52, v53
	v_add_f32_e32 v53, v54, v55
	v_add_f32_e32 v54, v57, v59
	v_add_f32_e32 v55, v61, v63
	v_add_f32_e32 v52, v52, v53
	v_add_f32_e32 v53, v54, v55
	v_add_f32_e32 v56, v52, v53
	ds_bpermute_b32 v57, v169, v56
	v_lshl_add_u64 v[52:53], s[92:93], 0, v[86:87]
	v_lshl_add_u64 v[54:55], v[152:153], 1, v[52:53]
	global_store_dwordx4 v[54:55], v[48:51], off
	s_waitcnt lgkmcnt(0)
	s_nop 0
	v_add_f32_e32 v48, v56, v57
	ds_bpermute_b32 v49, v112, v48
	v_cvt_pk_bf16_f32 v50, v78, v80
	v_cvt_pk_bf16_f32 v51, v82, v83
	v_cvt_pk_bf16_f32 v52, v79, v81
	v_cvt_pk_bf16_f32 v53, v84, v85
	global_store_dwordx4 v[54:55], v[50:53], off offset:256
	s_and_saveexec_b64 s[28:29], s[8:9]
	s_cbranch_execz .LBB0_2903
	s_waitcnt lgkmcnt(0)
	v_add_f32_e32 v50, v48, v49
	v_lshlrev_b64 v[48:49], 6, v[76:77]
	v_lshl_add_u64 v[48:49], s[0:1], 0, v[48:49]
	v_lshl_add_u64 v[48:49], s[26:27], 2, v[48:49]
	s_lshl_b32 s2, s38, 2
	v_lshl_add_u64 v[48:49], v[48:49], 0, s[2:3]
	global_store_dword v[48:49], v50, off
.LBB0_2903:
	s_or_b64 exec, exec, s[28:29]
	s_waitcnt vmcnt(12) lgkmcnt(0)
	v_and_b32_e32 v49, 0xffff0000, v216
	v_lshlrev_b32_e32 v48, 16, v216
	v_and_b32_e32 v51, 0xffff0000, v217
	v_lshlrev_b32_e32 v52, 16, v218
	v_add_f32_e32 v45, v45, v49
	v_lshlrev_b32_e32 v50, 16, v217
	v_add_f32_e32 v44, v44, v48
	v_add_f32_e32 v48, v40, v52
	v_add_f32_e32 v47, v47, v51
	v_cvt_pk_bf16_f32 v40, v44, v45
	v_mul_f32_e32 v45, v45, v45
	v_and_b32_e32 v53, 0xffff0000, v218
	v_and_b32_e32 v55, 0xffff0000, v219
	v_add_f32_e32 v46, v46, v50
	v_fmac_f32_e32 v45, v44, v44
	v_mul_f32_e32 v44, v47, v47
	v_lshlrev_b32_e32 v54, 16, v219
	v_add_f32_e32 v49, v41, v53
	v_add_f32_e32 v51, v43, v55
	v_fmac_f32_e32 v44, v46, v46
	v_add_f32_e32 v50, v42, v54
	v_cvt_pk_bf16_f32 v41, v46, v47
	v_add_f32_e32 v44, v45, v44
	v_mul_f32_e32 v45, v49, v49
	v_mul_f32_e32 v46, v51, v51
	v_fmac_f32_e32 v45, v48, v48
	v_fmac_f32_e32 v46, v50, v50
	v_cvt_pk_bf16_f32 v42, v48, v49
	v_add_f32_e32 v45, v45, v46
	s_waitcnt vmcnt(12)
	v_and_b32_e32 v46, 0xffff0000, v228
	v_and_b32_e32 v48, 0xffff0000, v229
	v_cvt_pk_bf16_f32 v43, v50, v51
	v_add_f32_e32 v44, v44, v45
	v_lshlrev_b32_e32 v45, 16, v228
	v_lshlrev_b32_e32 v47, 16, v229
	v_lshlrev_b32_e32 v49, 16, v230
	v_and_b32_e32 v50, 0xffff0000, v230
	v_add_f32_e32 v37, v37, v46
	v_add_f32_e32 v48, v39, v48
	v_and_b32_e32 v52, 0xffff0000, v231
	v_add_f32_e32 v36, v36, v45
	v_add_f32_e32 v45, v32, v49
	v_add_f32_e32 v46, v33, v50
	v_add_f32_e32 v47, v38, v47
	v_mul_f32_e32 v32, v37, v37
	v_mul_f32_e32 v33, v48, v48
	v_lshlrev_b32_e32 v51, 16, v231
	v_add_f32_e32 v50, v35, v52
	v_fmac_f32_e32 v32, v36, v36
	v_fmac_f32_e32 v33, v47, v47
	v_add_f32_e32 v49, v34, v51
	v_add_f32_e32 v32, v32, v33
	v_mul_f32_e32 v33, v46, v46
	v_mul_f32_e32 v34, v50, v50
	v_fmac_f32_e32 v33, v45, v45
	v_fmac_f32_e32 v34, v49, v49
	v_add_f32_e32 v33, v33, v34
	v_add_f32_e32 v32, v32, v33
	v_add_f32_e32 v35, v44, v32
	ds_bpermute_b32 v44, v169, v35
	v_lshl_add_u64 v[32:33], s[92:93], 0, v[74:75]
	v_lshl_add_u64 v[38:39], v[152:153], 1, v[32:33]
	global_store_dwordx4 v[38:39], v[40:43], off
	v_cvt_pk_bf16_f32 v34, v36, v37
	s_waitcnt lgkmcnt(0)
	v_add_f32_e32 v32, v35, v44
	ds_bpermute_b32 v33, v112, v32
	v_cvt_pk_bf16_f32 v35, v47, v48
	v_cvt_pk_bf16_f32 v36, v45, v46
	v_cvt_pk_bf16_f32 v37, v49, v50
	global_store_dwordx4 v[38:39], v[34:37], off offset:256
	s_and_saveexec_b64 s[28:29], s[8:9]
	s_cbranch_execz .LBB0_2905
	s_waitcnt lgkmcnt(0)
	v_add_f32_e32 v34, v32, v33
	v_lshlrev_b64 v[32:33], 6, v[72:73]
	v_lshl_add_u64 v[32:33], s[0:1], 0, v[32:33]
	v_lshl_add_u64 v[32:33], s[26:27], 2, v[32:33]
	s_lshl_b32 s2, s38, 2
	v_lshl_add_u64 v[32:33], v[32:33], 0, s[2:3]
	global_store_dword v[32:33], v34, off
;     __device__ __forceinline__ void operator()(const f32x4 (&acc)[2][2][4][2], const Unit& u, int wr, int wc, int fr, int fq) const {
;     ...
;                     const size_t off = (size_t)(u.pm * BM + ai * HALF + wr * 64 + (2 * mh + m2) * 16 + fr) * 1024 + col0 + bj * HALF;
;                     if (!basef) bh[m2][bj] = *(const u32x4*)(xin + off);
;                 }
; #pragma unroll
;             for (int m2 = 0; m2 < 2; ++m2) {
;                 const int m = 2 * mh + m2;
;                 const int row = u.pm * BM + ai * HALF + wr * 64 + m * 16 + fr; float sq = 0.f;
;                 if (basef) {
; #pragma unroll
;                     for (int bj = 0; bj < 2; ++bj) { const size_t off = (size_t)row * 1024 + col0 + bj * HALF; bf[m2][bj][0] = *(const f32x4*)(basef + off); bf[m2][bj][1] = *(const f32x4*)(basef + off + 4); }
;                 }
; #pragma unroll
;                 for (int bj = 0; bj < 2; ++bj) {
;                     const size_t off = (size_t)row * 1024 + col0 + bj * HALF;
;                     float bv[8];
;                     if (basef) { const f32x4 b0 = bf[m2][bj][0], b1 = bf[m2][bj][1]; bv[0] = b0[0]; bv[1] = b0[1]; bv[2] = b0[2]; bv[3] = b0[3]; bv[4] = b1[0]; bv[5] = b1[1]; bv[6] = b1[2]; bv[7] = b1[3]; }
;                     else { const u32x4 gw = bh[m2][bj];
;                         bv[0] = __uint_as_float(gw.x << 16); bv[1] = __uint_as_float(gw.x & 0xffff0000u); bv[2] = __uint_as_float(gw.y << 16); bv[3] = __uint_as_float(gw.y & 0xffff0000u);
;                         bv[4] = __uint_as_float(gw.z << 16); bv[5] = __uint_as_float(gw.z & 0xffff0000u); bv[6] = __uint_as_float(gw.w << 16); bv[7] = __uint_as_float(gw.w & 0xffff0000u); }
;                     float y[8];
; #pragma unroll
;                     for (int e = 0; e < 4; ++e) { y[e] = bv[e] + alpha * acc[ai][bj][m][0][e]; y[4 + e] = bv[4 + e] + alpha * acc[ai][bj][m][1][e]; }
;                     u32x4 w; w.x = cvt_pk_bf16(y[0], y[1]); w.y = cvt_pk_bf16(y[2], y[3]); w.z = cvt_pk_bf16(y[4], y[5]); w.w = cvt_pk_bf16(y[6], y[7]);
;                     *(u32x4*)(xs + off) = w;
;                     if (ss) sq += ((y[0] * y[0] + y[1] * y[1]) + (y[2] * y[2] + y[3] * y[3])) + ((y[4] * y[4] + y[5] * y[5]) + (y[6] * y[6] + y[7] * y[7]));
;                 }
.LBB0_2905:
	s_or_b64 exec, exec, s[28:29]
	v_add_u32_e32 v44, 0xa0, v154
	v_ashrrev_i32_e32 v45, 31, v44
	v_lshlrev_b64 v[54:55], 11, v[44:45]
	s_waitcnt lgkmcnt(0)
	v_lshl_add_u64 v[32:33], v[156:157], 0, v[54:55]
	v_add_u32_e32 v40, 0xb0, v154
	v_ashrrev_i32_e32 v41, 31, v40
	v_lshlrev_b64 v[42:43], 11, v[40:41]
	v_lshl_add_u64 v[32:33], v[156:157], 0, v[42:43]
	s_nop 0
	s_waitcnt vmcnt(12)
	v_lshlrev_b32_e32 v56, 16, v232
	v_and_b32_e32 v46, 0xffff0000, v232
	v_lshlrev_b32_e32 v57, 16, v233
	v_and_b32_e32 v47, 0xffff0000, v233
	v_lshlrev_b32_e32 v58, 16, v234
	v_and_b32_e32 v48, 0xffff0000, v234
	v_lshlrev_b32_e32 v59, 16, v235
	v_and_b32_e32 v49, 0xffff0000, v235
	s_waitcnt vmcnt(12)
	v_lshlrev_b32_e32 v60, 16, v236
	v_and_b32_e32 v50, 0xffff0000, v236
	v_lshlrev_b32_e32 v61, 16, v237
	v_and_b32_e32 v51, 0xffff0000, v237
	v_lshlrev_b32_e32 v62, 16, v238
	v_and_b32_e32 v52, 0xffff0000, v238
	v_lshlrev_b32_e32 v63, 16, v239
	v_and_b32_e32 v53, 0xffff0000, v239
	v_add_f32_e32 v29, v29, v46
	v_add_f32_e32 v25, v25, v48
	v_add_f32_e32 v31, v31, v47
	v_add_f32_e32 v27, v27, v49
	v_add_f32_e32 v48, v21, v50
	v_add_f32_e32 v49, v17, v52
	v_add_f32_e32 v51, v23, v51
	v_add_f32_e32 v53, v19, v53
	v_add_f32_e32 v28, v28, v56
	v_add_f32_e32 v24, v24, v58
	v_add_f32_e32 v30, v30, v57
	v_add_f32_e32 v26, v26, v59
	v_add_f32_e32 v46, v20, v60
	v_add_f32_e32 v47, v16, v62
	v_add_f32_e32 v50, v22, v61
	v_add_f32_e32 v52, v18, v63
	v_cvt_pk_bf16_f32 v16, v28, v29
	v_cvt_pk_bf16_f32 v17, v30, v31
	v_cvt_pk_bf16_f32 v18, v24, v25
	v_cvt_pk_bf16_f32 v19, v26, v27
	v_mul_f32_e32 v20, v29, v29
	v_mul_f32_e32 v21, v31, v31
	v_mul_f32_e32 v22, v25, v25
	v_mul_f32_e32 v23, v27, v27
	v_mul_f32_e32 v25, v48, v48
	v_mul_f32_e32 v27, v51, v51
	v_mul_f32_e32 v29, v49, v49
	v_mul_f32_e32 v31, v53, v53
	v_fmac_f32_e32 v20, v28, v28
	v_fmac_f32_e32 v21, v30, v30
	v_fmac_f32_e32 v22, v24, v24
	v_fmac_f32_e32 v23, v26, v26
	v_fmac_f32_e32 v25, v46, v46
	v_fmac_f32_e32 v27, v50, v50
	v_fmac_f32_e32 v29, v47, v47
	v_fmac_f32_e32 v31, v52, v52
	v_add_f32_e32 v20, v20, v21
	v_add_f32_e32 v21, v22, v23
	v_add_f32_e32 v22, v25, v27
	v_add_f32_e32 v23, v29, v31
	v_add_f32_e32 v20, v20, v21
	v_add_f32_e32 v21, v22, v23
	v_add_f32_e32 v24, v20, v21
	ds_bpermute_b32 v25, v169, v24
	v_lshl_add_u64 v[20:21], s[92:93], 0, v[54:55]
	v_lshl_add_u64 v[22:23], v[152:153], 1, v[20:21]
	global_store_dwordx4 v[22:23], v[16:19], off
	s_waitcnt lgkmcnt(0)
	s_nop 0
	v_add_f32_e32 v16, v24, v25
	ds_bpermute_b32 v17, v112, v16
	v_cvt_pk_bf16_f32 v18, v46, v48
	v_cvt_pk_bf16_f32 v19, v50, v51
	v_cvt_pk_bf16_f32 v20, v47, v49
	v_cvt_pk_bf16_f32 v21, v52, v53
	global_store_dwordx4 v[22:23], v[18:21], off offset:256
	s_and_saveexec_b64 s[28:29], s[8:9]
	s_cbranch_execz .LBB0_2907
	s_waitcnt lgkmcnt(0)
	v_add_f32_e32 v18, v16, v17
	v_lshlrev_b64 v[16:17], 6, v[44:45]
	v_lshl_add_u64 v[16:17], s[0:1], 0, v[16:17]
	v_lshl_add_u64 v[16:17], s[26:27], 2, v[16:17]
	s_lshl_b32 s2, s38, 2
	v_lshl_add_u64 v[16:17], v[16:17], 0, s[2:3]
	global_store_dword v[16:17], v18, off
.LBB0_2907:
	s_or_b64 exec, exec, s[28:29]
	s_waitcnt vmcnt(12) lgkmcnt(0)
	v_and_b32_e32 v17, 0xffff0000, v240
	v_lshlrev_b32_e32 v16, 16, v240
	v_and_b32_e32 v19, 0xffff0000, v241
	v_lshlrev_b32_e32 v20, 16, v242
	v_add_f32_e32 v13, v13, v17
	v_lshlrev_b32_e32 v18, 16, v241
	v_add_f32_e32 v12, v12, v16
	v_add_f32_e32 v16, v8, v20
	v_add_f32_e32 v15, v15, v19
	v_cvt_pk_bf16_f32 v8, v12, v13
	v_mul_f32_e32 v13, v13, v13
	v_and_b32_e32 v21, 0xffff0000, v242
	v_and_b32_e32 v23, 0xffff0000, v243
	v_add_f32_e32 v14, v14, v18
	v_fmac_f32_e32 v13, v12, v12
	v_mul_f32_e32 v12, v15, v15
	v_lshlrev_b32_e32 v22, 16, v243
	v_add_f32_e32 v17, v9, v21
	v_add_f32_e32 v19, v11, v23
	v_fmac_f32_e32 v12, v14, v14
	v_add_f32_e32 v18, v10, v22
	v_cvt_pk_bf16_f32 v9, v14, v15
	v_add_f32_e32 v12, v13, v12
	v_mul_f32_e32 v13, v17, v17
	v_mul_f32_e32 v14, v19, v19
	v_fmac_f32_e32 v13, v16, v16
	v_fmac_f32_e32 v14, v18, v18
	v_cvt_pk_bf16_f32 v10, v16, v17
	v_add_f32_e32 v13, v13, v14
	s_waitcnt vmcnt(12)
	v_and_b32_e32 v14, 0xffff0000, v244
	v_and_b32_e32 v16, 0xffff0000, v245
	v_cvt_pk_bf16_f32 v11, v18, v19
	v_add_f32_e32 v12, v12, v13
	v_lshlrev_b32_e32 v13, 16, v244
	v_lshlrev_b32_e32 v15, 16, v245
	v_lshlrev_b32_e32 v17, 16, v246
	v_and_b32_e32 v18, 0xffff0000, v246
	v_add_f32_e32 v5, v5, v14
	v_add_f32_e32 v16, v7, v16
	v_and_b32_e32 v20, 0xffff0000, v247
	v_add_f32_e32 v4, v4, v13
	v_add_f32_e32 v13, v0, v17
	v_add_f32_e32 v14, v1, v18
	v_add_f32_e32 v15, v6, v15
	v_mul_f32_e32 v0, v5, v5
	v_mul_f32_e32 v1, v16, v16
	v_lshlrev_b32_e32 v19, 16, v247
	v_add_f32_e32 v18, v3, v20
	v_fmac_f32_e32 v0, v4, v4
	v_fmac_f32_e32 v1, v15, v15
	v_add_f32_e32 v17, v2, v19
	v_add_f32_e32 v0, v0, v1
	v_mul_f32_e32 v1, v14, v14
	v_mul_f32_e32 v2, v18, v18
	v_fmac_f32_e32 v1, v13, v13
	v_fmac_f32_e32 v2, v17, v17
	v_add_f32_e32 v1, v1, v2
	v_add_f32_e32 v0, v0, v1
	v_add_f32_e32 v3, v12, v0
	ds_bpermute_b32 v12, v169, v3
	v_lshl_add_u64 v[0:1], s[92:93], 0, v[42:43]
	v_lshl_add_u64 v[6:7], v[152:153], 1, v[0:1]
	global_store_dwordx4 v[6:7], v[8:11], off
	v_cvt_pk_bf16_f32 v2, v4, v5
	s_waitcnt lgkmcnt(0)
	v_add_f32_e32 v0, v3, v12
	ds_bpermute_b32 v1, v112, v0
	v_cvt_pk_bf16_f32 v3, v15, v16
	v_cvt_pk_bf16_f32 v4, v13, v14
	v_cvt_pk_bf16_f32 v5, v17, v18
	global_store_dwordx4 v[6:7], v[2:5], off offset:256
	s_and_saveexec_b64 s[28:29], s[8:9]
	s_cbranch_execz .LBB0_2909
	s_waitcnt lgkmcnt(0)
	v_add_f32_e32 v2, v0, v1
	v_lshlrev_b64 v[0:1], 6, v[40:41]
	v_lshl_add_u64 v[0:1], s[0:1], 0, v[0:1]
	v_lshl_add_u64 v[0:1], s[26:27], 2, v[0:1]
	s_lshl_b32 s2, s38, 2
	v_lshl_add_u64 v[0:1], v[0:1], 0, s[2:3]
	global_store_dword v[0:1], v2, off

;     __device__ __forceinline__ void operator()(const f32x4 (&acc)[2][2][4][2], const Unit& u, int wr, int wc, int fr, int fq) const {
;         const int col0 = u.pn * BM + wc * 32 + 8 * fq;
; #pragma unroll
;         for (int ai = 0; ai < 2; ++ai)
; #pragma unroll
;         for (int mh = 0; mh < 2; ++mh) {
;             f32x4 bf[2][2][2]; u32x4 bh[2][2];
; #pragma unroll
;             for (int m2 = 0; m2 < 2; ++m2)
; #pragma unroll
;                 for (int bj = 0; bj < 2; ++bj) {
;                     const size_t off = (size_t)(u.pm * BM + ai * HALF + wr * 64 + (2 * mh + m2) * 16 + fr) * 1024 + col0 + bj * HALF;
;                     if (!basef) bh[m2][bj] = *(const u32x4*)(xin + off);
;                 }
; #pragma unroll
;             for (int m2 = 0; m2 < 2; ++m2) {
;                 const int m = 2 * mh + m2;
;                 const int row = u.pm * BM + ai * HALF + wr * 64 + m * 16 + fr; float sq = 0.f;
;                 if (basef) {
; #pragma unroll
;                     for (int bj = 0; bj < 2; ++bj) { const size_t off = (size_t)row * 1024 + col0 + bj * HALF; bf[m2][bj][0] = *(const f32x4*)(basef + off); bf[m2][bj][1] = *(const f32x4*)(basef + off + 4); }
;                 }
; #pragma unroll
;                 for (int bj = 0; bj < 2; ++bj) {
;                     const size_t off = (size_t)row * 1024 + col0 + bj * HALF;
;                     float bv[8];
;                     if (basef) { const f32x4 b0 = bf[m2][bj][0], b1 = bf[m2][bj][1]; bv[0] = b0[0]; bv[1] = b0[1]; bv[2] = b0[2]; bv[3] = b0[3]; bv[4] = b1[0]; bv[5] = b1[1]; bv[6] = b1[2]; bv[7] = b1[3]; }
;                     else { const u32x4 gw = bh[m2][bj];
;                         bv[0] = __uint_as_float(gw.x << 16); bv[1] = __uint_as_float(gw.x & 0xffff0000u); bv[2] = __uint_as_float(gw.y << 16); bv[3] = __uint_as_float(gw.y & 0xffff0000u);
;                         bv[4] = __uint_as_float(gw.z << 16); bv[5] = __uint_as_float(gw.z & 0xffff0000u); bv[6] = __uint_as_float(gw.w << 16); bv[7] = __uint_as_float(gw.w & 0xffff0000u); }
;                     float y[8];
; #pragma unroll
;                     for (int e = 0; e < 4; ++e) { y[e] = bv[e] + alpha * acc[ai][bj][m][0][e]; y[4 + e] = bv[4 + e] + alpha * acc[ai][bj][m][1][e]; }
;                     u32x4 w; w.x = cvt_pk_bf16(y[0], y[1]); w.y = cvt_pk_bf16(y[2], y[3]); w.z = cvt_pk_bf16(y[4], y[5]); w.w = cvt_pk_bf16(y[6], y[7]);
.LBB0_3107:
	v_lshl_or_b32 v152, s49, 8, v164
	v_lshl_add_u32 v154, s4, 8, v162
	v_ashrrev_i32_e32 v153, 31, v152
	v_lshlrev_b64 v[178:179], 1, v[152:153]
	v_ashrrev_i32_e32 v155, 31, v154
	v_lshl_add_u64 v[156:157], s[92:93], 0, v[178:179]
	v_lshlrev_b64 v[180:181], 11, v[154:155]
	v_lshl_add_u64 v[128:129], v[156:157], 0, v[180:181]
	v_lshl_add_u64 v[248:249], v[156:157], 0, v[180:181]
	global_load_dwordx4 v[170:173], v[128:129], off
	global_load_dwordx4 v[174:177], v[128:129], off offset:256
	v_or_b32_e32 v158, 16, v154
	v_ashrrev_i32_e32 v159, 31, v158
	v_lshlrev_b64 v[160:161], 11, v[158:159]
	v_lshl_add_u64 v[128:129], v[156:157], 0, v[160:161]
	global_load_dwordx4 v[132:135], v[128:129], off
	s_nop 0
	global_load_dwordx4 v[128:131], v[128:129], off offset:256
	s_mov_b32 s99, 0
	s_mov_b32 s98, 0x10000
	v_lshl_add_u64 v[250:251], v[248:249], 0, s[98:99]
	global_load_dwordx4 v[190:193], v[250:251], off
	global_load_dwordx4 v[194:197], v[250:251], off offset:256
	s_mov_b32 s98, 0x8000
	v_lshl_add_u64 v[248:249], v[250:251], 0, s[98:99]
	global_load_dwordx4 v[200:203], v[248:249], off
	global_load_dwordx4 v[204:207], v[248:249], off offset:256
	s_mov_b32 s98, 0x28000
	v_lshl_add_u64 v[250:251], v[248:249], 0, s[98:99]
	global_load_dwordx4 v[208:211], v[250:251], off
	global_load_dwordx4 v[212:215], v[250:251], off offset:256
	s_mov_b32 s98, 0x8000
	v_lshl_add_u64 v[248:249], v[250:251], 0, s[98:99]
	global_load_dwordx4 v[216:219], v[248:249], off
	global_load_dwordx4 v[228:231], v[248:249], off offset:256
	s_mov_b32 s98, 0x8000
	v_lshl_add_u64 v[250:251], v[248:249], 0, s[98:99]
	global_load_dwordx4 v[232:235], v[250:251], off
	global_load_dwordx4 v[236:239], v[250:251], off offset:256
	s_mov_b32 s98, 0x8000
	v_lshl_add_u64 v[248:249], v[250:251], 0, s[98:99]
	global_load_dwordx4 v[240:243], v[248:249], off
	global_load_dwordx4 v[244:247], v[248:249], off offset:256
	v_and_b32_e32 v182, 64, v168
	v_xor_b32_e32 v169, 16, v168
	v_add_u32_e32 v182, 64, v182
	v_xor_b32_e32 v183, 32, v168
	v_cmp_lt_i32_e32 vcc, v169, v182
	v_lshl_add_u64 v[180:181], s[90:91], 0, v[180:181]
	v_lshl_add_u64 v[178:179], v[180:181], 0, v[178:179]
	v_cndmask_b32_e32 v169, v168, v169, vcc
	v_cmp_lt_i32_e32 vcc, v183, v182
	v_lshlrev_b32_e32 v169, 2, v169
	s_lshl_b32 s28, s49, 2
	v_cndmask_b32_e32 v182, v168, v183, vcc
	s_ashr_i32 s29, s28, 31
	s_waitcnt vmcnt(12)
	v_lshlrev_b32_e32 v180, 16, v170
	v_and_b32_e32 v170, 0xffff0000, v170
	v_lshlrev_b32_e32 v181, 16, v171
	v_and_b32_e32 v171, 0xffff0000, v171
	v_lshlrev_b32_e32 v183, 16, v172
	v_and_b32_e32 v172, 0xffff0000, v172
	v_lshlrev_b32_e32 v184, 16, v173
	v_and_b32_e32 v173, 0xffff0000, v173
	v_lshlrev_b32_e32 v185, 16, v174
	v_and_b32_e32 v174, 0xffff0000, v174
	v_lshlrev_b32_e32 v186, 16, v175
	v_and_b32_e32 v175, 0xffff0000, v175
	v_lshlrev_b32_e32 v187, 16, v176
	v_and_b32_e32 v176, 0xffff0000, v176
	v_lshlrev_b32_e32 v188, 16, v177
	v_and_b32_e32 v177, 0xffff0000, v177
	v_add_f32_e32 v125, v125, v170
	v_add_f32_e32 v121, v121, v172
	v_add_f32_e32 v127, v127, v171
	v_add_f32_e32 v123, v123, v173
	v_add_f32_e32 v117, v117, v174
	v_add_f32_e32 v171, v113, v176
	v_add_f32_e32 v119, v119, v175
	v_add_f32_e32 v173, v115, v177
	v_add_f32_e32 v124, v124, v180
	v_add_f32_e32 v120, v120, v183
	v_add_f32_e32 v126, v126, v181
	v_add_f32_e32 v122, v122, v184
	v_add_f32_e32 v116, v116, v185
	v_add_f32_e32 v170, v112, v187
	v_add_f32_e32 v118, v118, v186
	v_add_f32_e32 v172, v114, v188
	v_cvt_pk_bf16_f32 v112, v124, v125
	v_cvt_pk_bf16_f32 v113, v126, v127
	v_mul_f32_e32 v114, v125, v125
	v_mul_f32_e32 v115, v127, v127
	v_mul_f32_e32 v125, v121, v121
	v_mul_f32_e32 v127, v123, v123
	v_mul_f32_e32 v174, v117, v117
	v_mul_f32_e32 v175, v119, v119
	v_mul_f32_e32 v176, v171, v171
	v_mul_f32_e32 v177, v173, v173
	v_fmac_f32_e32 v114, v124, v124
	v_fmac_f32_e32 v115, v126, v126
	v_fmac_f32_e32 v125, v120, v120
	v_fmac_f32_e32 v127, v122, v122
	v_fmac_f32_e32 v174, v116, v116
	v_fmac_f32_e32 v175, v118, v118
	v_fmac_f32_e32 v176, v170, v170
	v_fmac_f32_e32 v177, v172, v172
	v_add_f32_e32 v114, v114, v115
	v_add_f32_e32 v115, v125, v127
	v_add_f32_e32 v124, v174, v175
	v_add_f32_e32 v125, v176, v177
	v_add_f32_e32 v114, v114, v115
	v_add_f32_e32 v115, v124, v125
	v_add_f32_e32 v124, v114, v115
	ds_bpermute_b32 v125, v169, v124
	v_cvt_pk_bf16_f32 v114, v120, v121
	v_cvt_pk_bf16_f32 v115, v122, v123
	global_store_dwordx4 v[178:179], v[112:115], off
	v_cvt_pk_bf16_f32 v116, v116, v117
	v_cvt_pk_bf16_f32 v117, v118, v119
	v_cvt_pk_bf16_f32 v118, v170, v171
	v_cvt_pk_bf16_f32 v119, v172, v173
	global_store_dwordx4 v[178:179], v[116:119], off offset:256
	s_waitcnt lgkmcnt(0)
	v_add_f32_e32 v113, v124, v125
	v_lshlrev_b32_e32 v112, 2, v182
	ds_bpermute_b32 v114, v112, v113
	s_and_saveexec_b64 s[30:31], s[8:9]
	s_cbranch_execz .LBB0_3109
	s_waitcnt lgkmcnt(0)
	v_add_f32_e32 v113, v113, v114
	v_lshlrev_b64 v[114:115], 6, v[154:155]
	v_lshl_add_u64 v[114:115], s[0:1], 0, v[114:115]
	v_lshl_add_u64 v[114:115], s[28:29], 2, v[114:115]
	s_lshl_b32 s4, s40, 2
	v_lshl_add_u64 v[114:115], v[114:115], 0, s[4:5]
	global_store_dword v[114:115], v113, off

;     __device__ __forceinline__ void operator()(const f32x4 (&acc)[2][2][4][2], const Unit& u, int wr, int wc, int fr, int fq) const {
;     ...
;                     const size_t off = (size_t)(u.pm * BM + ai * HALF + wr * 64 + (2 * mh + m2) * 16 + fr) * 1024 + col0 + bj * HALF;
;                     if (!basef) bh[m2][bj] = *(const u32x4*)(xin + off);
;                 }
; #pragma unroll
;             for (int m2 = 0; m2 < 2; ++m2) {
;                 const int m = 2 * mh + m2;
;                 const int row = u.pm * BM + ai * HALF + wr * 64 + m * 16 + fr; float sq = 0.f;
;                 if (basef) {
; #pragma unroll
;                     for (int bj = 0; bj < 2; ++bj) { const size_t off = (size_t)row * 1024 + col0 + bj * HALF; bf[m2][bj][0] = *(const f32x4*)(basef + off); bf[m2][bj][1] = *(const f32x4*)(basef + off + 4); }
;                 }
; #pragma unroll
;                 for (int bj = 0; bj < 2; ++bj) {
;                     const size_t off = (size_t)row * 1024 + col0 + bj * HALF;
;                     float bv[8];
;                     if (basef) { const f32x4 b0 = bf[m2][bj][0], b1 = bf[m2][bj][1]; bv[0] = b0[0]; bv[1] = b0[1]; bv[2] = b0[2]; bv[3] = b0[3]; bv[4] = b1[0]; bv[5] = b1[1]; bv[6] = b1[2]; bv[7] = b1[3]; }
;                     else { const u32x4 gw = bh[m2][bj];
;                         bv[0] = __uint_as_float(gw.x << 16); bv[1] = __uint_as_float(gw.x & 0xffff0000u); bv[2] = __uint_as_float(gw.y << 16); bv[3] = __uint_as_float(gw.y & 0xffff0000u);
;                         bv[4] = __uint_as_float(gw.z << 16); bv[5] = __uint_as_float(gw.z & 0xffff0000u); bv[6] = __uint_as_float(gw.w << 16); bv[7] = __uint_as_float(gw.w & 0xffff0000u); }
;                     float y[8];
; #pragma unroll
;                     for (int e = 0; e < 4; ++e) { y[e] = bv[e] + alpha * acc[ai][bj][m][0][e]; y[4 + e] = bv[4 + e] + alpha * acc[ai][bj][m][1][e]; }
;                     u32x4 w; w.x = cvt_pk_bf16(y[0], y[1]); w.y = cvt_pk_bf16(y[2], y[3]); w.z = cvt_pk_bf16(y[4], y[5]); w.w = cvt_pk_bf16(y[6], y[7]);
;                     *(u32x4*)(xs + off) = w;
;                     if (ss) sq += ((y[0] * y[0] + y[1] * y[1]) + (y[2] * y[2] + y[3] * y[3])) + ((y[4] * y[4] + y[5] * y[5]) + (y[6] * y[6] + y[7] * y[7]));
;                 }
.LBB0_3111:
	s_or_b64 exec, exec, s[30:31]
	v_or_b32_e32 v108, 32, v154
	v_ashrrev_i32_e32 v109, 31, v108
	v_lshlrev_b64 v[110:111], 11, v[108:109]
	s_waitcnt lgkmcnt(0)
	v_lshl_add_u64 v[96:97], v[156:157], 0, v[110:111]
	v_or_b32_e32 v104, 48, v154
	v_ashrrev_i32_e32 v105, 31, v104
	v_lshlrev_b64 v[106:107], 11, v[104:105]
	v_lshl_add_u64 v[96:97], v[156:157], 0, v[106:107]
	s_nop 0
	s_waitcnt vmcnt(12)
	v_lshlrev_b32_e32 v113, 16, v190
	v_and_b32_e32 v114, 0xffff0000, v190
	v_lshlrev_b32_e32 v122, 16, v191
	v_and_b32_e32 v115, 0xffff0000, v191
	v_lshlrev_b32_e32 v123, 16, v192
	v_and_b32_e32 v116, 0xffff0000, v192
	v_lshlrev_b32_e32 v124, 16, v193
	v_and_b32_e32 v117, 0xffff0000, v193
	s_waitcnt vmcnt(12)
	v_lshlrev_b32_e32 v125, 16, v194
	v_and_b32_e32 v118, 0xffff0000, v194
	v_lshlrev_b32_e32 v126, 16, v195
	v_and_b32_e32 v119, 0xffff0000, v195
	v_lshlrev_b32_e32 v127, 16, v196
	v_and_b32_e32 v120, 0xffff0000, v196
	v_lshlrev_b32_e32 v128, 16, v197
	v_and_b32_e32 v121, 0xffff0000, v197
	v_add_f32_e32 v93, v93, v114
	v_add_f32_e32 v89, v89, v116
	v_add_f32_e32 v95, v95, v115
	v_add_f32_e32 v91, v91, v117
	v_add_f32_e32 v115, v85, v118
	v_add_f32_e32 v116, v81, v120
	v_add_f32_e32 v119, v87, v119
	v_add_f32_e32 v120, v83, v121
	v_add_f32_e32 v92, v92, v113
	v_add_f32_e32 v88, v88, v123
	v_add_f32_e32 v94, v94, v122
	v_add_f32_e32 v90, v90, v124
	v_add_f32_e32 v113, v84, v125
	v_add_f32_e32 v114, v80, v127
	v_add_f32_e32 v117, v86, v126
	v_add_f32_e32 v118, v82, v128
	v_cvt_pk_bf16_f32 v80, v92, v93
	v_cvt_pk_bf16_f32 v81, v94, v95
	v_cvt_pk_bf16_f32 v82, v88, v89
	v_cvt_pk_bf16_f32 v83, v90, v91
	v_mul_f32_e32 v84, v93, v93
	v_mul_f32_e32 v85, v95, v95
	v_mul_f32_e32 v86, v89, v89
	v_mul_f32_e32 v87, v91, v91
	v_mul_f32_e32 v89, v115, v115
	v_mul_f32_e32 v91, v119, v119
	v_mul_f32_e32 v93, v116, v116
	v_mul_f32_e32 v95, v120, v120
	v_fmac_f32_e32 v84, v92, v92
	v_fmac_f32_e32 v85, v94, v94
	v_fmac_f32_e32 v86, v88, v88
	v_fmac_f32_e32 v87, v90, v90
	v_fmac_f32_e32 v89, v113, v113
	v_fmac_f32_e32 v91, v117, v117
	v_fmac_f32_e32 v93, v114, v114
	v_fmac_f32_e32 v95, v118, v118
	v_add_f32_e32 v84, v84, v85
	v_add_f32_e32 v85, v86, v87
	v_add_f32_e32 v86, v89, v91
	v_add_f32_e32 v87, v93, v95
	v_add_f32_e32 v84, v84, v85
	v_add_f32_e32 v85, v86, v87
	v_add_f32_e32 v88, v84, v85
	ds_bpermute_b32 v89, v169, v88
	v_lshl_add_u64 v[84:85], s[90:91], 0, v[110:111]
	v_lshl_add_u64 v[86:87], v[152:153], 1, v[84:85]
	global_store_dwordx4 v[86:87], v[80:83], off
	s_waitcnt lgkmcnt(0)
	s_nop 0
	v_add_f32_e32 v80, v88, v89
	ds_bpermute_b32 v81, v112, v80
	v_cvt_pk_bf16_f32 v82, v113, v115
	v_cvt_pk_bf16_f32 v83, v117, v119
	v_cvt_pk_bf16_f32 v84, v114, v116
	v_cvt_pk_bf16_f32 v85, v118, v120
	global_store_dwordx4 v[86:87], v[82:85], off offset:256
	s_and_saveexec_b64 s[30:31], s[8:9]
	s_cbranch_execz .LBB0_3113
	s_waitcnt lgkmcnt(0)
	v_add_f32_e32 v82, v80, v81
	v_lshlrev_b64 v[80:81], 6, v[108:109]
	v_lshl_add_u64 v[80:81], s[0:1], 0, v[80:81]
	v_lshl_add_u64 v[80:81], s[28:29], 2, v[80:81]
	s_lshl_b32 s4, s40, 2
	v_lshl_add_u64 v[80:81], v[80:81], 0, s[4:5]
	global_store_dword v[80:81], v82, off
.LBB0_3113:
	s_or_b64 exec, exec, s[30:31]
	s_waitcnt vmcnt(12) lgkmcnt(0)
	v_and_b32_e32 v81, 0xffff0000, v200
	v_lshlrev_b32_e32 v80, 16, v200
	v_and_b32_e32 v83, 0xffff0000, v201
	v_lshlrev_b32_e32 v84, 16, v202
	v_add_f32_e32 v77, v77, v81
	v_lshlrev_b32_e32 v82, 16, v201
	v_add_f32_e32 v76, v76, v80
	v_add_f32_e32 v80, v72, v84
	v_add_f32_e32 v79, v79, v83
	v_cvt_pk_bf16_f32 v72, v76, v77
	v_mul_f32_e32 v77, v77, v77
	v_and_b32_e32 v85, 0xffff0000, v202
	v_and_b32_e32 v87, 0xffff0000, v203
	v_add_f32_e32 v78, v78, v82
	v_fmac_f32_e32 v77, v76, v76
	v_mul_f32_e32 v76, v79, v79
	v_lshlrev_b32_e32 v86, 16, v203
	v_add_f32_e32 v81, v73, v85
	v_add_f32_e32 v83, v75, v87
	v_fmac_f32_e32 v76, v78, v78
	v_add_f32_e32 v82, v74, v86
	v_cvt_pk_bf16_f32 v73, v78, v79
	v_add_f32_e32 v76, v77, v76
	v_mul_f32_e32 v77, v81, v81
	v_mul_f32_e32 v78, v83, v83
	v_fmac_f32_e32 v77, v80, v80
	v_fmac_f32_e32 v78, v82, v82
	v_cvt_pk_bf16_f32 v74, v80, v81
	v_add_f32_e32 v77, v77, v78
	s_waitcnt vmcnt(12)
	v_and_b32_e32 v78, 0xffff0000, v204
	v_and_b32_e32 v80, 0xffff0000, v205
	v_cvt_pk_bf16_f32 v75, v82, v83
	v_add_f32_e32 v76, v76, v77
	v_lshlrev_b32_e32 v77, 16, v204
	v_lshlrev_b32_e32 v79, 16, v205
	v_lshlrev_b32_e32 v81, 16, v206
	v_and_b32_e32 v82, 0xffff0000, v206
	v_add_f32_e32 v69, v69, v78
	v_add_f32_e32 v80, v71, v80
	v_and_b32_e32 v84, 0xffff0000, v207
	v_add_f32_e32 v68, v68, v77
	v_add_f32_e32 v77, v64, v81
	v_add_f32_e32 v78, v65, v82
	v_add_f32_e32 v79, v70, v79
	v_mul_f32_e32 v64, v69, v69
	v_mul_f32_e32 v65, v80, v80
	v_lshlrev_b32_e32 v83, 16, v207
	v_add_f32_e32 v82, v67, v84
	v_fmac_f32_e32 v64, v68, v68
	v_fmac_f32_e32 v65, v79, v79
	v_add_f32_e32 v81, v66, v83
	v_add_f32_e32 v64, v64, v65
	v_mul_f32_e32 v65, v78, v78
	v_mul_f32_e32 v66, v82, v82
	v_fmac_f32_e32 v65, v77, v77
	v_fmac_f32_e32 v66, v81, v81
	v_add_f32_e32 v65, v65, v66
	v_add_f32_e32 v64, v64, v65
	v_add_f32_e32 v67, v76, v64
	ds_bpermute_b32 v76, v169, v67
	v_lshl_add_u64 v[64:65], s[90:91], 0, v[106:107]
	v_lshl_add_u64 v[70:71], v[152:153], 1, v[64:65]
	global_store_dwordx4 v[70:71], v[72:75], off
	v_cvt_pk_bf16_f32 v66, v68, v69
	s_waitcnt lgkmcnt(0)
	v_add_f32_e32 v64, v67, v76
	ds_bpermute_b32 v65, v112, v64
	v_cvt_pk_bf16_f32 v67, v79, v80
	v_cvt_pk_bf16_f32 v68, v77, v78
	v_cvt_pk_bf16_f32 v69, v81, v82
	global_store_dwordx4 v[70:71], v[66:69], off offset:256
	s_and_saveexec_b64 s[30:31], s[8:9]
	s_cbranch_execz .LBB0_3115
	s_waitcnt lgkmcnt(0)
	v_add_f32_e32 v66, v64, v65
	v_lshlrev_b64 v[64:65], 6, v[104:105]
	v_lshl_add_u64 v[64:65], s[0:1], 0, v[64:65]
	v_lshl_add_u64 v[64:65], s[28:29], 2, v[64:65]
	s_lshl_b32 s4, s40, 2
	v_lshl_add_u64 v[64:65], v[64:65], 0, s[4:5]
	global_store_dword v[64:65], v66, off
;     __device__ __forceinline__ void operator()(const f32x4 (&acc)[2][2][4][2], const Unit& u, int wr, int wc, int fr, int fq) const {
;     ...
;                     const size_t off = (size_t)(u.pm * BM + ai * HALF + wr * 64 + (2 * mh + m2) * 16 + fr) * 1024 + col0 + bj * HALF;
;                     if (!basef) bh[m2][bj] = *(const u32x4*)(xin + off);
;                 }
; #pragma unroll
;             for (int m2 = 0; m2 < 2; ++m2) {
;                 const int m = 2 * mh + m2;
;                 const int row = u.pm * BM + ai * HALF + wr * 64 + m * 16 + fr; float sq = 0.f;
;                 if (basef) {
; #pragma unroll
;                     for (int bj = 0; bj < 2; ++bj) { const size_t off = (size_t)row * 1024 + col0 + bj * HALF; bf[m2][bj][0] = *(const f32x4*)(basef + off); bf[m2][bj][1] = *(const f32x4*)(basef + off + 4); }
;                 }
; #pragma unroll
;                 for (int bj = 0; bj < 2; ++bj) {
;                     const size_t off = (size_t)row * 1024 + col0 + bj * HALF;
;                     float bv[8];
;                     if (basef) { const f32x4 b0 = bf[m2][bj][0], b1 = bf[m2][bj][1]; bv[0] = b0[0]; bv[1] = b0[1]; bv[2] = b0[2]; bv[3] = b0[3]; bv[4] = b1[0]; bv[5] = b1[1]; bv[6] = b1[2]; bv[7] = b1[3]; }
;                     else { const u32x4 gw = bh[m2][bj];
;                         bv[0] = __uint_as_float(gw.x << 16); bv[1] = __uint_as_float(gw.x & 0xffff0000u); bv[2] = __uint_as_float(gw.y << 16); bv[3] = __uint_as_float(gw.y & 0xffff0000u);
;                         bv[4] = __uint_as_float(gw.z << 16); bv[5] = __uint_as_float(gw.z & 0xffff0000u); bv[6] = __uint_as_float(gw.w << 16); bv[7] = __uint_as_float(gw.w & 0xffff0000u); }
;                     float y[8];
; #pragma unroll
;                     for (int e = 0; e < 4; ++e) { y[e] = bv[e] + alpha * acc[ai][bj][m][0][e]; y[4 + e] = bv[4 + e] + alpha * acc[ai][bj][m][1][e]; }
;                     u32x4 w; w.x = cvt_pk_bf16(y[0], y[1]); w.y = cvt_pk_bf16(y[2], y[3]); w.z = cvt_pk_bf16(y[4], y[5]); w.w = cvt_pk_bf16(y[6], y[7]);
;                     *(u32x4*)(xs + off) = w;
;                     if (ss) sq += ((y[0] * y[0] + y[1] * y[1]) + (y[2] * y[2] + y[3] * y[3])) + ((y[4] * y[4] + y[5] * y[5]) + (y[6] * y[6] + y[7] * y[7]));
;                 }
.LBB0_3115:
	s_or_b64 exec, exec, s[30:31]
	v_add_u32_e32 v76, 0x80, v154
	v_ashrrev_i32_e32 v77, 31, v76
	v_lshlrev_b64 v[86:87], 11, v[76:77]
	s_waitcnt lgkmcnt(0)
	v_lshl_add_u64 v[64:65], v[156:157], 0, v[86:87]
	v_add_u32_e32 v72, 0x90, v154
	v_ashrrev_i32_e32 v73, 31, v72
	v_lshlrev_b64 v[74:75], 11, v[72:73]
	v_lshl_add_u64 v[64:65], v[156:157], 0, v[74:75]
	s_nop 0
	s_waitcnt vmcnt(12)
	v_lshlrev_b32_e32 v88, 16, v208
	v_and_b32_e32 v78, 0xffff0000, v208
	v_lshlrev_b32_e32 v89, 16, v209
	v_and_b32_e32 v79, 0xffff0000, v209
	v_lshlrev_b32_e32 v90, 16, v210
	v_and_b32_e32 v80, 0xffff0000, v210
	v_lshlrev_b32_e32 v91, 16, v211
	v_and_b32_e32 v81, 0xffff0000, v211
	s_waitcnt vmcnt(12)
	v_lshlrev_b32_e32 v92, 16, v212
	v_and_b32_e32 v82, 0xffff0000, v212
	v_lshlrev_b32_e32 v93, 16, v213
	v_and_b32_e32 v83, 0xffff0000, v213
	v_lshlrev_b32_e32 v94, 16, v214
	v_and_b32_e32 v84, 0xffff0000, v214
	v_lshlrev_b32_e32 v95, 16, v215
	v_and_b32_e32 v85, 0xffff0000, v215
	v_add_f32_e32 v61, v61, v78
	v_add_f32_e32 v57, v57, v80
	v_add_f32_e32 v63, v63, v79
	v_add_f32_e32 v59, v59, v81
	v_add_f32_e32 v80, v53, v82
	v_add_f32_e32 v81, v49, v84
	v_add_f32_e32 v83, v55, v83
	v_add_f32_e32 v85, v51, v85
	v_add_f32_e32 v60, v60, v88
	v_add_f32_e32 v56, v56, v90
	v_add_f32_e32 v62, v62, v89
	v_add_f32_e32 v58, v58, v91
	v_add_f32_e32 v78, v52, v92
	v_add_f32_e32 v79, v48, v94
	v_add_f32_e32 v82, v54, v93
	v_add_f32_e32 v84, v50, v95
	v_cvt_pk_bf16_f32 v48, v60, v61
	v_cvt_pk_bf16_f32 v49, v62, v63
	v_cvt_pk_bf16_f32 v50, v56, v57
	v_cvt_pk_bf16_f32 v51, v58, v59
	v_mul_f32_e32 v52, v61, v61
	v_mul_f32_e32 v53, v63, v63
	v_mul_f32_e32 v54, v57, v57
	v_mul_f32_e32 v55, v59, v59
	v_mul_f32_e32 v57, v80, v80
	v_mul_f32_e32 v59, v83, v83
	v_mul_f32_e32 v61, v81, v81
	v_mul_f32_e32 v63, v85, v85
	v_fmac_f32_e32 v52, v60, v60
	v_fmac_f32_e32 v53, v62, v62
	v_fmac_f32_e32 v54, v56, v56
	v_fmac_f32_e32 v55, v58, v58
	v_fmac_f32_e32 v57, v78, v78
	v_fmac_f32_e32 v59, v82, v82
	v_fmac_f32_e32 v61, v79, v79
	v_fmac_f32_e32 v63, v84, v84
	v_add_f32_e32 v52, v52, v53
	v_add_f32_e32 v53, v54, v55
	v_add_f32_e32 v54, v57, v59
	v_add_f32_e32 v55, v61, v63
	v_add_f32_e32 v52, v52, v53
	v_add_f32_e32 v53, v54, v55
	v_add_f32_e32 v56, v52, v53
	ds_bpermute_b32 v57, v169, v56
	v_lshl_add_u64 v[52:53], s[90:91], 0, v[86:87]
	v_lshl_add_u64 v[54:55], v[152:153], 1, v[52:53]
	global_store_dwordx4 v[54:55], v[48:51], off
	s_waitcnt lgkmcnt(0)
	s_nop 0
	v_add_f32_e32 v48, v56, v57
	ds_bpermute_b32 v49, v112, v48
	v_cvt_pk_bf16_f32 v50, v78, v80
	v_cvt_pk_bf16_f32 v51, v82, v83
	v_cvt_pk_bf16_f32 v52, v79, v81
	v_cvt_pk_bf16_f32 v53, v84, v85
	global_store_dwordx4 v[54:55], v[50:53], off offset:256
	s_and_saveexec_b64 s[30:31], s[8:9]
	s_cbranch_execz .LBB0_3117
	s_waitcnt lgkmcnt(0)
	v_add_f32_e32 v50, v48, v49
	v_lshlrev_b64 v[48:49], 6, v[76:77]
	v_lshl_add_u64 v[48:49], s[0:1], 0, v[48:49]
	v_lshl_add_u64 v[48:49], s[28:29], 2, v[48:49]
	s_lshl_b32 s4, s40, 2
	v_lshl_add_u64 v[48:49], v[48:49], 0, s[4:5]
	global_store_dword v[48:49], v50, off
.LBB0_3117:
	s_or_b64 exec, exec, s[30:31]
	s_waitcnt vmcnt(12) lgkmcnt(0)
	v_and_b32_e32 v49, 0xffff0000, v216
	v_lshlrev_b32_e32 v48, 16, v216
	v_and_b32_e32 v51, 0xffff0000, v217
	v_lshlrev_b32_e32 v52, 16, v218
	v_add_f32_e32 v45, v45, v49
	v_lshlrev_b32_e32 v50, 16, v217
	v_add_f32_e32 v44, v44, v48
	v_add_f32_e32 v48, v40, v52
	v_add_f32_e32 v47, v47, v51
	v_cvt_pk_bf16_f32 v40, v44, v45
	v_mul_f32_e32 v45, v45, v45
	v_and_b32_e32 v53, 0xffff0000, v218
	v_and_b32_e32 v55, 0xffff0000, v219
	v_add_f32_e32 v46, v46, v50
	v_fmac_f32_e32 v45, v44, v44
	v_mul_f32_e32 v44, v47, v47
	v_lshlrev_b32_e32 v54, 16, v219
	v_add_f32_e32 v49, v41, v53
	v_add_f32_e32 v51, v43, v55
	v_fmac_f32_e32 v44, v46, v46
	v_add_f32_e32 v50, v42, v54
	v_cvt_pk_bf16_f32 v41, v46, v47
	v_add_f32_e32 v44, v45, v44
	v_mul_f32_e32 v45, v49, v49
	v_mul_f32_e32 v46, v51, v51
	v_fmac_f32_e32 v45, v48, v48
	v_fmac_f32_e32 v46, v50, v50
	v_cvt_pk_bf16_f32 v42, v48, v49
	v_add_f32_e32 v45, v45, v46
	s_waitcnt vmcnt(12)
	v_and_b32_e32 v46, 0xffff0000, v228
	v_and_b32_e32 v48, 0xffff0000, v229
	v_cvt_pk_bf16_f32 v43, v50, v51
	v_add_f32_e32 v44, v44, v45
	v_lshlrev_b32_e32 v45, 16, v228
	v_lshlrev_b32_e32 v47, 16, v229
	v_lshlrev_b32_e32 v49, 16, v230
	v_and_b32_e32 v50, 0xffff0000, v230
	v_add_f32_e32 v37, v37, v46
	v_add_f32_e32 v48, v39, v48
	v_and_b32_e32 v52, 0xffff0000, v231
	v_add_f32_e32 v36, v36, v45
	v_add_f32_e32 v45, v32, v49
	v_add_f32_e32 v46, v33, v50
	v_add_f32_e32 v47, v38, v47
	v_mul_f32_e32 v32, v37, v37
	v_mul_f32_e32 v33, v48, v48
	v_lshlrev_b32_e32 v51, 16, v231
	v_add_f32_e32 v50, v35, v52
	v_fmac_f32_e32 v32, v36, v36
	v_fmac_f32_e32 v33, v47, v47
	v_add_f32_e32 v49, v34, v51
	v_add_f32_e32 v32, v32, v33
	v_mul_f32_e32 v33, v46, v46
	v_mul_f32_e32 v34, v50, v50
	v_fmac_f32_e32 v33, v45, v45
	v_fmac_f32_e32 v34, v49, v49
	v_add_f32_e32 v33, v33, v34
	v_add_f32_e32 v32, v32, v33
	v_add_f32_e32 v35, v44, v32
	ds_bpermute_b32 v44, v169, v35
	v_lshl_add_u64 v[32:33], s[90:91], 0, v[74:75]
	v_lshl_add_u64 v[38:39], v[152:153], 1, v[32:33]
	global_store_dwordx4 v[38:39], v[40:43], off
	v_cvt_pk_bf16_f32 v34, v36, v37
	s_waitcnt lgkmcnt(0)
	v_add_f32_e32 v32, v35, v44
	ds_bpermute_b32 v33, v112, v32
	v_cvt_pk_bf16_f32 v35, v47, v48
	v_cvt_pk_bf16_f32 v36, v45, v46
	v_cvt_pk_bf16_f32 v37, v49, v50
	global_store_dwordx4 v[38:39], v[34:37], off offset:256
	s_and_saveexec_b64 s[30:31], s[8:9]
	s_cbranch_execz .LBB0_3119
	s_waitcnt lgkmcnt(0)
	v_add_f32_e32 v34, v32, v33
	v_lshlrev_b64 v[32:33], 6, v[72:73]
	v_lshl_add_u64 v[32:33], s[0:1], 0, v[32:33]
	v_lshl_add_u64 v[32:33], s[28:29], 2, v[32:33]
	s_lshl_b32 s4, s40, 2
	v_lshl_add_u64 v[32:33], v[32:33], 0, s[4:5]
	global_store_dword v[32:33], v34, off
;     __device__ __forceinline__ void operator()(const f32x4 (&acc)[2][2][4][2], const Unit& u, int wr, int wc, int fr, int fq) const {
;     ...
;                     const size_t off = (size_t)(u.pm * BM + ai * HALF + wr * 64 + (2 * mh + m2) * 16 + fr) * 1024 + col0 + bj * HALF;
;                     if (!basef) bh[m2][bj] = *(const u32x4*)(xin + off);
;                 }
; #pragma unroll
;             for (int m2 = 0; m2 < 2; ++m2) {
;                 const int m = 2 * mh + m2;
;                 const int row = u.pm * BM + ai * HALF + wr * 64 + m * 16 + fr; float sq = 0.f;
;                 if (basef) {
; #pragma unroll
;                     for (int bj = 0; bj < 2; ++bj) { const size_t off = (size_t)row * 1024 + col0 + bj * HALF; bf[m2][bj][0] = *(const f32x4*)(basef + off); bf[m2][bj][1] = *(const f32x4*)(basef + off + 4); }
;                 }
; #pragma unroll
;                 for (int bj = 0; bj < 2; ++bj) {
;                     const size_t off = (size_t)row * 1024 + col0 + bj * HALF;
;                     float bv[8];
;                     if (basef) { const f32x4 b0 = bf[m2][bj][0], b1 = bf[m2][bj][1]; bv[0] = b0[0]; bv[1] = b0[1]; bv[2] = b0[2]; bv[3] = b0[3]; bv[4] = b1[0]; bv[5] = b1[1]; bv[6] = b1[2]; bv[7] = b1[3]; }
;                     else { const u32x4 gw = bh[m2][bj];
;                         bv[0] = __uint_as_float(gw.x << 16); bv[1] = __uint_as_float(gw.x & 0xffff0000u); bv[2] = __uint_as_float(gw.y << 16); bv[3] = __uint_as_float(gw.y & 0xffff0000u);
;                         bv[4] = __uint_as_float(gw.z << 16); bv[5] = __uint_as_float(gw.z & 0xffff0000u); bv[6] = __uint_as_float(gw.w << 16); bv[7] = __uint_as_float(gw.w & 0xffff0000u); }
;                     float y[8];
; #pragma unroll
;                     for (int e = 0; e < 4; ++e) { y[e] = bv[e] + alpha * acc[ai][bj][m][0][e]; y[4 + e] = bv[4 + e] + alpha * acc[ai][bj][m][1][e]; }
;                     u32x4 w; w.x = cvt_pk_bf16(y[0], y[1]); w.y = cvt_pk_bf16(y[2], y[3]); w.z = cvt_pk_bf16(y[4], y[5]); w.w = cvt_pk_bf16(y[6], y[7]);
;                     *(u32x4*)(xs + off) = w;
;                     if (ss) sq += ((y[0] * y[0] + y[1] * y[1]) + (y[2] * y[2] + y[3] * y[3])) + ((y[4] * y[4] + y[5] * y[5]) + (y[6] * y[6] + y[7] * y[7]));
;                 }
.LBB0_3119:
	s_or_b64 exec, exec, s[30:31]
	v_add_u32_e32 v44, 0xa0, v154
	v_ashrrev_i32_e32 v45, 31, v44
	v_lshlrev_b64 v[54:55], 11, v[44:45]
	s_waitcnt lgkmcnt(0)
	v_lshl_add_u64 v[32:33], v[156:157], 0, v[54:55]
	v_add_u32_e32 v40, 0xb0, v154
	v_ashrrev_i32_e32 v41, 31, v40
	v_lshlrev_b64 v[42:43], 11, v[40:41]
	v_lshl_add_u64 v[32:33], v[156:157], 0, v[42:43]
	s_nop 0
	s_waitcnt vmcnt(12)
	v_lshlrev_b32_e32 v56, 16, v232
	v_and_b32_e32 v46, 0xffff0000, v232
	v_lshlrev_b32_e32 v57, 16, v233
	v_and_b32_e32 v47, 0xffff0000, v233
	v_lshlrev_b32_e32 v58, 16, v234
	v_and_b32_e32 v48, 0xffff0000, v234
	v_lshlrev_b32_e32 v59, 16, v235
	v_and_b32_e32 v49, 0xffff0000, v235
	s_waitcnt vmcnt(12)
	v_lshlrev_b32_e32 v60, 16, v236
	v_and_b32_e32 v50, 0xffff0000, v236
	v_lshlrev_b32_e32 v61, 16, v237
	v_and_b32_e32 v51, 0xffff0000, v237
	v_lshlrev_b32_e32 v62, 16, v238
	v_and_b32_e32 v52, 0xffff0000, v238
	v_lshlrev_b32_e32 v63, 16, v239
	v_and_b32_e32 v53, 0xffff0000, v239
	v_add_f32_e32 v29, v29, v46
	v_add_f32_e32 v25, v25, v48
	v_add_f32_e32 v31, v31, v47
	v_add_f32_e32 v27, v27, v49
	v_add_f32_e32 v48, v21, v50
	v_add_f32_e32 v49, v17, v52
	v_add_f32_e32 v51, v23, v51
	v_add_f32_e32 v53, v19, v53
	v_add_f32_e32 v28, v28, v56
	v_add_f32_e32 v24, v24, v58
	v_add_f32_e32 v30, v30, v57
	v_add_f32_e32 v26, v26, v59
	v_add_f32_e32 v46, v20, v60
	v_add_f32_e32 v47, v16, v62
	v_add_f32_e32 v50, v22, v61
	v_add_f32_e32 v52, v18, v63
	v_cvt_pk_bf16_f32 v16, v28, v29
	v_cvt_pk_bf16_f32 v17, v30, v31
	v_cvt_pk_bf16_f32 v18, v24, v25
	v_cvt_pk_bf16_f32 v19, v26, v27
	v_mul_f32_e32 v20, v29, v29
	v_mul_f32_e32 v21, v31, v31
	v_mul_f32_e32 v22, v25, v25
	v_mul_f32_e32 v23, v27, v27
	v_mul_f32_e32 v25, v48, v48
	v_mul_f32_e32 v27, v51, v51
	v_mul_f32_e32 v29, v49, v49
	v_mul_f32_e32 v31, v53, v53
	v_fmac_f32_e32 v20, v28, v28
	v_fmac_f32_e32 v21, v30, v30
	v_fmac_f32_e32 v22, v24, v24
	v_fmac_f32_e32 v23, v26, v26
	v_fmac_f32_e32 v25, v46, v46
	v_fmac_f32_e32 v27, v50, v50
	v_fmac_f32_e32 v29, v47, v47
	v_fmac_f32_e32 v31, v52, v52
	v_add_f32_e32 v20, v20, v21
	v_add_f32_e32 v21, v22, v23
	v_add_f32_e32 v22, v25, v27
	v_add_f32_e32 v23, v29, v31
	v_add_f32_e32 v20, v20, v21
	v_add_f32_e32 v21, v22, v23
	v_add_f32_e32 v24, v20, v21
	ds_bpermute_b32 v25, v169, v24
	v_lshl_add_u64 v[20:21], s[90:91], 0, v[54:55]
	v_lshl_add_u64 v[22:23], v[152:153], 1, v[20:21]
	global_store_dwordx4 v[22:23], v[16:19], off
	s_waitcnt lgkmcnt(0)
	s_nop 0
	v_add_f32_e32 v16, v24, v25
	ds_bpermute_b32 v17, v112, v16
	v_cvt_pk_bf16_f32 v18, v46, v48
	v_cvt_pk_bf16_f32 v19, v50, v51
	v_cvt_pk_bf16_f32 v20, v47, v49
	v_cvt_pk_bf16_f32 v21, v52, v53
	global_store_dwordx4 v[22:23], v[18:21], off offset:256
	s_and_saveexec_b64 s[30:31], s[8:9]
	s_cbranch_execz .LBB0_3121
	s_waitcnt lgkmcnt(0)
	v_add_f32_e32 v18, v16, v17
	v_lshlrev_b64 v[16:17], 6, v[44:45]
	v_lshl_add_u64 v[16:17], s[0:1], 0, v[16:17]
	v_lshl_add_u64 v[16:17], s[28:29], 2, v[16:17]
	s_lshl_b32 s4, s40, 2
	v_lshl_add_u64 v[16:17], v[16:17], 0, s[4:5]
	global_store_dword v[16:17], v18, off
.LBB0_3121:
	s_or_b64 exec, exec, s[30:31]
	s_waitcnt vmcnt(12) lgkmcnt(0)
	v_and_b32_e32 v17, 0xffff0000, v240
	v_lshlrev_b32_e32 v16, 16, v240
	v_and_b32_e32 v19, 0xffff0000, v241
	v_lshlrev_b32_e32 v20, 16, v242
	v_add_f32_e32 v13, v13, v17
	v_lshlrev_b32_e32 v18, 16, v241
	v_add_f32_e32 v12, v12, v16
	v_add_f32_e32 v16, v8, v20
	v_add_f32_e32 v15, v15, v19
	v_cvt_pk_bf16_f32 v8, v12, v13
	v_mul_f32_e32 v13, v13, v13
	v_and_b32_e32 v21, 0xffff0000, v242
	v_and_b32_e32 v23, 0xffff0000, v243
	v_add_f32_e32 v14, v14, v18
	v_fmac_f32_e32 v13, v12, v12
	v_mul_f32_e32 v12, v15, v15
	v_lshlrev_b32_e32 v22, 16, v243
	v_add_f32_e32 v17, v9, v21
	v_add_f32_e32 v19, v11, v23
	v_fmac_f32_e32 v12, v14, v14
	v_add_f32_e32 v18, v10, v22
	v_cvt_pk_bf16_f32 v9, v14, v15
	v_add_f32_e32 v12, v13, v12
	v_mul_f32_e32 v13, v17, v17
	v_mul_f32_e32 v14, v19, v19
	v_fmac_f32_e32 v13, v16, v16
	v_fmac_f32_e32 v14, v18, v18
	v_cvt_pk_bf16_f32 v10, v16, v17
	v_add_f32_e32 v13, v13, v14
	s_waitcnt vmcnt(12)
	v_and_b32_e32 v14, 0xffff0000, v244
	v_and_b32_e32 v16, 0xffff0000, v245
	v_cvt_pk_bf16_f32 v11, v18, v19
	v_add_f32_e32 v12, v12, v13
	v_lshlrev_b32_e32 v13, 16, v244
	v_lshlrev_b32_e32 v15, 16, v245
	v_lshlrev_b32_e32 v17, 16, v246
	v_and_b32_e32 v18, 0xffff0000, v246
	v_add_f32_e32 v5, v5, v14
	v_add_f32_e32 v16, v7, v16
	v_and_b32_e32 v20, 0xffff0000, v247
	v_add_f32_e32 v4, v4, v13
	v_add_f32_e32 v13, v0, v17
	v_add_f32_e32 v14, v1, v18
	v_add_f32_e32 v15, v6, v15
	v_mul_f32_e32 v0, v5, v5
	v_mul_f32_e32 v1, v16, v16
	v_lshlrev_b32_e32 v19, 16, v247
	v_add_f32_e32 v18, v3, v20
	v_fmac_f32_e32 v0, v4, v4
	v_fmac_f32_e32 v1, v15, v15
	v_add_f32_e32 v17, v2, v19
	v_add_f32_e32 v0, v0, v1
	v_mul_f32_e32 v1, v14, v14
	v_mul_f32_e32 v2, v18, v18
	v_fmac_f32_e32 v1, v13, v13
	v_fmac_f32_e32 v2, v17, v17
	v_add_f32_e32 v1, v1, v2
	v_add_f32_e32 v0, v0, v1
	v_add_f32_e32 v3, v12, v0
	ds_bpermute_b32 v12, v169, v3
	v_lshl_add_u64 v[0:1], s[90:91], 0, v[42:43]
	v_lshl_add_u64 v[6:7], v[152:153], 1, v[0:1]
	global_store_dwordx4 v[6:7], v[8:11], off
	v_cvt_pk_bf16_f32 v2, v4, v5
	s_waitcnt lgkmcnt(0)
	v_add_f32_e32 v0, v3, v12
	ds_bpermute_b32 v1, v112, v0
	v_cvt_pk_bf16_f32 v3, v15, v16
	v_cvt_pk_bf16_f32 v4, v13, v14
	v_cvt_pk_bf16_f32 v5, v17, v18
	global_store_dwordx4 v[6:7], v[2:5], off offset:256
	s_and_saveexec_b64 s[30:31], s[8:9]
	s_cbranch_execz .LBB0_3123
	s_waitcnt lgkmcnt(0)
	v_add_f32_e32 v2, v0, v1
	v_lshlrev_b64 v[0:1], 6, v[40:41]
	v_lshl_add_u64 v[0:1], s[0:1], 0, v[0:1]
	v_lshl_add_u64 v[0:1], s[28:29], 2, v[0:1]
	s_lshl_b32 s4, s40, 2
	v_lshl_add_u64 v[0:1], v[0:1], 0, s[4:5]
	global_store_dword v[0:1], v2, off

;     __device__ __forceinline__ void operator()(const f32x4 (&acc)[2][2][4][2], const Unit& u, int wr, int wc, int fr, int fq) const {
;     ...
;                     const size_t off = (size_t)(u.pm * BM + ai * HALF + wr * 64 + (2 * mh + m2) * 16 + fr) * 1024 + col0 + bj * HALF;
;                     if (!basef) bh[m2][bj] = *(const u32x4*)(xin + off);
;                 }
; #pragma unroll
;             for (int m2 = 0; m2 < 2; ++m2) {
;                 const int m = 2 * mh + m2;
;                 const int row = u.pm * BM + ai * HALF + wr * 64 + m * 16 + fr; float sq = 0.f;
;                 if (basef) {
; #pragma unroll
;                     for (int bj = 0; bj < 2; ++bj) { const size_t off = (size_t)row * 1024 + col0 + bj * HALF; bf[m2][bj][0] = *(const f32x4*)(basef + off); bf[m2][bj][1] = *(const f32x4*)(basef + off + 4); }
;                 }
; #pragma unroll
;                 for (int bj = 0; bj < 2; ++bj) {
;                     const size_t off = (size_t)row * 1024 + col0 + bj * HALF;
;                     float bv[8];
;                     if (basef) { const f32x4 b0 = bf[m2][bj][0], b1 = bf[m2][bj][1]; bv[0] = b0[0]; bv[1] = b0[1]; bv[2] = b0[2]; bv[3] = b0[3]; bv[4] = b1[0]; bv[5] = b1[1]; bv[6] = b1[2]; bv[7] = b1[3]; }
;                     else { const u32x4 gw = bh[m2][bj];
;                         bv[0] = __uint_as_float(gw.x << 16); bv[1] = __uint_as_float(gw.x & 0xffff0000u); bv[2] = __uint_as_float(gw.y << 16); bv[3] = __uint_as_float(gw.y & 0xffff0000u);
;                         bv[4] = __uint_as_float(gw.z << 16); bv[5] = __uint_as_float(gw.z & 0xffff0000u); bv[6] = __uint_as_float(gw.w << 16); bv[7] = __uint_as_float(gw.w & 0xffff0000u); }
;                     float y[8];
; #pragma unroll
;                     for (int e = 0; e < 4; ++e) { y[e] = bv[e] + alpha * acc[ai][bj][m][0][e]; y[4 + e] = bv[4 + e] + alpha * acc[ai][bj][m][1][e]; }
;                     u32x4 w; w.x = cvt_pk_bf16(y[0], y[1]); w.y = cvt_pk_bf16(y[2], y[3]); w.z = cvt_pk_bf16(y[4], y[5]); w.w = cvt_pk_bf16(y[6], y[7]);
;                     *(u32x4*)(xs + off) = w;
;                     if (ss) sq += ((y[0] * y[0] + y[1] * y[1]) + (y[2] * y[2] + y[3] * y[3])) + ((y[4] * y[4] + y[5] * y[5]) + (y[6] * y[6] + y[7] * y[7]));
;                 }
.LBB0_3267:
	v_lshl_or_b32 v144, s41, 8, v152
	v_lshl_add_u32 v148, s40, 8, v150
	v_ashrrev_i32_e32 v145, 31, v144
	v_or_b32_e32 v164, 16, v148
	v_lshlrev_b64 v[144:145], 1, v[144:145]
	v_ashrrev_i32_e32 v149, 31, v148
	v_ashrrev_i32_e32 v165, 31, v164
	v_lshl_add_u64 v[146:147], s[90:91], 0, v[144:145]
	v_lshlrev_b64 v[172:173], 11, v[148:149]
	v_lshlrev_b64 v[174:175], 11, v[164:165]
	v_lshl_add_u64 v[160:161], v[146:147], 0, v[172:173]
	v_lshl_add_u64 v[244:245], v[146:147], 0, v[172:173]
	v_lshl_add_u64 v[168:169], v[146:147], 0, v[174:175]
	global_load_dwordx4 v[156:159], v[160:161], off
	s_nop 0
	global_load_dwordx4 v[160:163], v[160:161], off offset:256
	s_nop 0
	global_load_dwordx4 v[164:167], v[168:169], off
	s_nop 0
	global_load_dwordx4 v[168:171], v[168:169], off offset:256
	s_mov_b32 s99, 0
	s_mov_b32 s98, 0x10000
	v_lshl_add_u64 v[248:249], v[244:245], 0, s[98:99]
	global_load_dwordx4 v[200:203], v[248:249], off offset:256
	global_load_dwordx4 v[192:195], v[248:249], off
	s_mov_b32 s98, 0x18000
	v_lshl_add_u64 v[246:247], v[244:245], 0, s[98:99]
	global_load_dwordx4 v[204:207], v[246:247], off
	global_load_dwordx4 v[208:211], v[246:247], off offset:256
	s_mov_b32 s98, 0x40000
	v_lshl_add_u64 v[248:249], v[244:245], 0, s[98:99]
	global_load_dwordx4 v[212:215], v[248:249], off
	global_load_dwordx4 v[220:223], v[248:249], off offset:256
	s_mov_b32 s98, 0x48000
	v_lshl_add_u64 v[246:247], v[244:245], 0, s[98:99]
	global_load_dwordx4 v[216:219], v[246:247], off
	global_load_dwordx4 v[224:227], v[246:247], off offset:256
	s_mov_b32 s98, 0x50000
	v_lshl_add_u64 v[248:249], v[244:245], 0, s[98:99]
	global_load_dwordx4 v[228:231], v[248:249], off
	global_load_dwordx4 v[232:235], v[248:249], off offset:256
	s_mov_b32 s98, 0x58000
	v_lshl_add_u64 v[246:247], v[244:245], 0, s[98:99]
	global_load_dwordx4 v[236:239], v[246:247], off
	global_load_dwordx4 v[240:243], v[246:247], off offset:256
	v_lshl_add_u64 v[172:173], s[92:93], 0, v[172:173]
	v_lshl_add_u64 v[172:173], v[172:173], 0, v[144:145]
	v_lshl_add_u64 v[174:175], s[92:93], 0, v[174:175]
	v_lshl_add_u64 v[174:175], v[174:175], 0, v[144:145]
	s_andn2_b64 vcc, exec, s[6:7]
	s_mov_b64 s[6:7], -1
	s_waitcnt vmcnt(12)
	v_lshlrev_b32_e32 v149, 16, v156
	v_and_b32_e32 v156, 0xffff0000, v156
	v_lshlrev_b32_e32 v176, 16, v157
	v_and_b32_e32 v157, 0xffff0000, v157
	v_lshlrev_b32_e32 v181, 16, v162
	v_and_b32_e32 v162, 0xffff0000, v162
	v_lshlrev_b32_e32 v187, 16, v168
	v_lshlrev_b32_e32 v177, 16, v158
	v_and_b32_e32 v158, 0xffff0000, v158
	v_lshlrev_b32_e32 v178, 16, v159
	v_and_b32_e32 v159, 0xffff0000, v159
	v_lshlrev_b32_e32 v179, 16, v160
	v_and_b32_e32 v160, 0xffff0000, v160
	v_lshlrev_b32_e32 v180, 16, v161
	v_and_b32_e32 v161, 0xffff0000, v161
	v_lshlrev_b32_e32 v182, 16, v163
	v_and_b32_e32 v163, 0xffff0000, v163
	v_and_b32_e32 v168, 0xffff0000, v168
	v_fmac_f32_e32 v149, 0.5, v124
	v_fmac_f32_e32 v156, 0.5, v125
	v_fmac_f32_e32 v176, 0.5, v126
	v_fmac_f32_e32 v157, 0.5, v127
	v_fmac_f32_e32 v181, 0.5, v104
	v_fmac_f32_e32 v162, 0.5, v105
	v_cvt_pk_bf16_f32 v104, v149, v156
	v_cvt_pk_bf16_f32 v105, v176, v157
	v_fmac_f32_e32 v187, 0.5, v100
	v_or_b32_e32 v100, 32, v148
	v_lshlrev_b32_e32 v183, 16, v164
	v_and_b32_e32 v164, 0xffff0000, v164
	v_lshlrev_b32_e32 v184, 16, v165
	v_and_b32_e32 v165, 0xffff0000, v165
	v_fmac_f32_e32 v177, 0.5, v120
	v_fmac_f32_e32 v158, 0.5, v121
	v_fmac_f32_e32 v178, 0.5, v122
	v_fmac_f32_e32 v159, 0.5, v123
	v_fmac_f32_e32 v179, 0.5, v108
	v_fmac_f32_e32 v160, 0.5, v109
	v_fmac_f32_e32 v180, 0.5, v110
	v_fmac_f32_e32 v182, 0.5, v106
	v_fmac_f32_e32 v161, 0.5, v111
	v_fmac_f32_e32 v163, 0.5, v107
	v_cvt_pk_bf16_f32 v106, v177, v158
	v_cvt_pk_bf16_f32 v107, v178, v159
	global_store_dwordx4 v[172:173], v[104:107], off
	v_fmac_f32_e32 v168, 0.5, v101
	v_ashrrev_i32_e32 v101, 31, v100
	v_cvt_pk_bf16_f32 v104, v179, v160
	v_cvt_pk_bf16_f32 v105, v180, v161
	v_lshlrev_b32_e32 v185, 16, v166
	v_and_b32_e32 v166, 0xffff0000, v166
	v_lshlrev_b32_e32 v186, 16, v167
	v_and_b32_e32 v167, 0xffff0000, v167
	v_fmac_f32_e32 v183, 0.5, v116
	v_fmac_f32_e32 v164, 0.5, v117
	v_fmac_f32_e32 v184, 0.5, v118
	v_fmac_f32_e32 v165, 0.5, v119
	v_cvt_pk_bf16_f32 v106, v181, v162
	v_cvt_pk_bf16_f32 v107, v182, v163
	global_store_dwordx4 v[172:173], v[104:107], off offset:256
	v_lshlrev_b64 v[116:117], 11, v[100:101]
	v_lshlrev_b32_e32 v188, 16, v169
	v_cvt_pk_bf16_f32 v104, v183, v164
	v_cvt_pk_bf16_f32 v105, v184, v165
	v_and_b32_e32 v169, 0xffff0000, v169
	v_lshlrev_b32_e32 v189, 16, v170
	v_and_b32_e32 v170, 0xffff0000, v170
	v_lshlrev_b32_e32 v190, 16, v171
	v_and_b32_e32 v171, 0xffff0000, v171
	v_fmac_f32_e32 v185, 0.5, v112
	v_fmac_f32_e32 v166, 0.5, v113
	v_fmac_f32_e32 v186, 0.5, v114
	v_fmac_f32_e32 v167, 0.5, v115
	v_cvt_pk_bf16_f32 v106, v185, v166
	v_cvt_pk_bf16_f32 v107, v186, v167
	global_store_dwordx4 v[174:175], v[104:107], off
	v_fmac_f32_e32 v189, 0.5, v96
	v_fmac_f32_e32 v170, 0.5, v97
	v_lshl_add_u64 v[104:105], v[146:147], 0, v[116:117]
	v_fmac_f32_e32 v188, 0.5, v102
	v_fmac_f32_e32 v190, 0.5, v98
	v_fmac_f32_e32 v169, 0.5, v103
	v_fmac_f32_e32 v171, 0.5, v99
	v_cvt_pk_bf16_f32 v96, v187, v168
	v_cvt_pk_bf16_f32 v97, v188, v169
	v_cvt_pk_bf16_f32 v98, v189, v170
	v_cvt_pk_bf16_f32 v99, v190, v171
	s_nop 0
	v_or_b32_e32 v108, 48, v148
	v_ashrrev_i32_e32 v109, 31, v108
	v_lshlrev_b64 v[118:119], 11, v[108:109]
	v_lshl_add_u64 v[112:113], v[146:147], 0, v[118:119]
	s_nop 0
	v_lshl_add_u64 v[116:117], s[92:93], 0, v[116:117]
	global_store_dwordx4 v[174:175], v[96:99], off offset:256
	v_lshl_add_u64 v[116:117], v[116:117], 0, v[144:145]
	s_waitcnt vmcnt(14)
;     __device__ __forceinline__ void operator()(const f32x4 (&acc)[2][2][4][2], const Unit& u, int wr, int wc, int fr, int fq) const {
;     ...
;                     const size_t off = (size_t)(u.pm * BM + ai * HALF + wr * 64 + (2 * mh + m2) * 16 + fr) * 1024 + col0 + bj * HALF;
;                     if (!basef) bh[m2][bj] = *(const u32x4*)(xin + off);
;                 }
; #pragma unroll
;             for (int m2 = 0; m2 < 2; ++m2) {
;                 const int m = 2 * mh + m2;
;                 const int row = u.pm * BM + ai * HALF + wr * 64 + m * 16 + fr; float sq = 0.f;
;                 if (basef) {
; #pragma unroll
;                     for (int bj = 0; bj < 2; ++bj) { const size_t off = (size_t)row * 1024 + col0 + bj * HALF; bf[m2][bj][0] = *(const f32x4*)(basef + off); bf[m2][bj][1] = *(const f32x4*)(basef + off + 4); }
;                 }
; #pragma unroll
;                 for (int bj = 0; bj < 2; ++bj) {
;                     const size_t off = (size_t)row * 1024 + col0 + bj * HALF;
;                     float bv[8];
;                     if (basef) { const f32x4 b0 = bf[m2][bj][0], b1 = bf[m2][bj][1]; bv[0] = b0[0]; bv[1] = b0[1]; bv[2] = b0[2]; bv[3] = b0[3]; bv[4] = b1[0]; bv[5] = b1[1]; bv[6] = b1[2]; bv[7] = b1[3]; }
;                     else { const u32x4 gw = bh[m2][bj];
;                         bv[0] = __uint_as_float(gw.x << 16); bv[1] = __uint_as_float(gw.x & 0xffff0000u); bv[2] = __uint_as_float(gw.y << 16); bv[3] = __uint_as_float(gw.y & 0xffff0000u);
;                         bv[4] = __uint_as_float(gw.z << 16); bv[5] = __uint_as_float(gw.z & 0xffff0000u); bv[6] = __uint_as_float(gw.w << 16); bv[7] = __uint_as_float(gw.w & 0xffff0000u); }
;                     float y[8];
; #pragma unroll
;                     for (int e = 0; e < 4; ++e) { y[e] = bv[e] + alpha * acc[ai][bj][m][0][e]; y[4 + e] = bv[4 + e] + alpha * acc[ai][bj][m][1][e]; }
;                     u32x4 w; w.x = cvt_pk_bf16(y[0], y[1]); w.y = cvt_pk_bf16(y[2], y[3]); w.z = cvt_pk_bf16(y[4], y[5]); w.w = cvt_pk_bf16(y[6], y[7]);
;                     *(u32x4*)(xs + off) = w;
;                     if (ss) sq += ((y[0] * y[0] + y[1] * y[1]) + (y[2] * y[2] + y[3] * y[3])) + ((y[4] * y[4] + y[5] * y[5]) + (y[6] * y[6] + y[7] * y[7]));
;                 }
	v_lshlrev_b32_e32 v122, 16, v202
	v_lshlrev_b32_e32 v96, 16, v192
	v_and_b32_e32 v97, 0xffff0000, v192
	v_lshlrev_b32_e32 v98, 16, v193
	v_and_b32_e32 v99, 0xffff0000, v193
	v_and_b32_e32 v106, 0xffff0000, v202
	v_lshlrev_b32_e32 v100, 16, v194
	v_and_b32_e32 v101, 0xffff0000, v194
	v_lshlrev_b32_e32 v102, 16, v195
	v_and_b32_e32 v103, 0xffff0000, v195
	v_lshlrev_b32_e32 v120, 16, v200
	v_and_b32_e32 v104, 0xffff0000, v200
	v_lshlrev_b32_e32 v121, 16, v201
	v_and_b32_e32 v105, 0xffff0000, v201
	v_lshlrev_b32_e32 v123, 16, v203
	v_and_b32_e32 v107, 0xffff0000, v203
	v_fmac_f32_e32 v96, 0.5, v92
	v_fmac_f32_e32 v97, 0.5, v93
	v_fmac_f32_e32 v98, 0.5, v94
	v_fmac_f32_e32 v99, 0.5, v95
	v_fmac_f32_e32 v122, 0.5, v76
	v_fmac_f32_e32 v106, 0.5, v77
	v_cvt_pk_bf16_f32 v76, v96, v97
	v_cvt_pk_bf16_f32 v77, v98, v99
	v_fmac_f32_e32 v100, 0.5, v88
	v_fmac_f32_e32 v101, 0.5, v89
	v_fmac_f32_e32 v102, 0.5, v90
	v_fmac_f32_e32 v103, 0.5, v91
	v_fmac_f32_e32 v120, 0.5, v80
	v_fmac_f32_e32 v104, 0.5, v81
	v_fmac_f32_e32 v121, 0.5, v82
	v_fmac_f32_e32 v123, 0.5, v78
	v_fmac_f32_e32 v105, 0.5, v83
	v_fmac_f32_e32 v107, 0.5, v79
	v_cvt_pk_bf16_f32 v78, v100, v101
	v_cvt_pk_bf16_f32 v79, v102, v103
	global_store_dwordx4 v[116:117], v[76:79], off
	s_waitcnt vmcnt(14)
	v_lshlrev_b32_e32 v124, 16, v204
	v_and_b32_e32 v108, 0xffff0000, v204
	v_cvt_pk_bf16_f32 v76, v120, v104
	v_cvt_pk_bf16_f32 v77, v121, v105
	v_lshlrev_b32_e32 v126, 16, v206
	v_cvt_pk_bf16_f32 v78, v122, v106
	v_cvt_pk_bf16_f32 v79, v123, v107
	global_store_dwordx4 v[116:117], v[76:79], off offset:256
	v_lshlrev_b32_e32 v125, 16, v205
	v_and_b32_e32 v109, 0xffff0000, v205
	v_lshl_add_u64 v[76:77], s[92:93], 0, v[118:119]
	v_and_b32_e32 v110, 0xffff0000, v206
	v_lshlrev_b32_e32 v127, 16, v207
	v_and_b32_e32 v111, 0xffff0000, v207
	v_fmac_f32_e32 v124, 0.5, v84
	v_fmac_f32_e32 v126, 0.5, v72
	v_fmac_f32_e32 v108, 0.5, v85
	v_cvt_pk_bf16_f32 v72, v124, v108
	v_lshl_add_u64 v[76:77], v[76:77], 0, v[144:145]
	v_fmac_f32_e32 v110, 0.5, v73
	v_fmac_f32_e32 v125, 0.5, v86
	v_fmac_f32_e32 v127, 0.5, v74
	v_fmac_f32_e32 v109, 0.5, v87
	v_fmac_f32_e32 v111, 0.5, v75
	v_cvt_pk_bf16_f32 v73, v125, v109
	v_cvt_pk_bf16_f32 v74, v126, v110
	v_cvt_pk_bf16_f32 v75, v127, v111
	global_store_dwordx4 v[76:77], v[72:75], off
	s_waitcnt vmcnt(15)
	v_lshlrev_b32_e32 v80, 16, v211
	v_and_b32_e32 v81, 0xffff0000, v211
	v_lshlrev_b32_e32 v72, 16, v208
	v_and_b32_e32 v73, 0xffff0000, v208
	v_fmac_f32_e32 v72, 0.5, v68
	v_add_u32_e32 v68, 0x80, v148
	v_lshlrev_b32_e32 v74, 16, v209
	v_and_b32_e32 v75, 0xffff0000, v209
	v_lshlrev_b32_e32 v78, 16, v210
	v_and_b32_e32 v79, 0xffff0000, v210
	v_fmac_f32_e32 v73, 0.5, v69
	v_fmac_f32_e32 v80, 0.5, v66
	v_fmac_f32_e32 v81, 0.5, v67
	v_ashrrev_i32_e32 v69, 31, v68
	v_fmac_f32_e32 v78, 0.5, v64
	v_fmac_f32_e32 v79, 0.5, v65
	v_fmac_f32_e32 v74, 0.5, v70
	v_fmac_f32_e32 v75, 0.5, v71
	v_cvt_pk_bf16_f32 v64, v72, v73
	v_cvt_pk_bf16_f32 v65, v74, v75
	v_cvt_pk_bf16_f32 v66, v78, v79
	v_cvt_pk_bf16_f32 v67, v80, v81
	v_lshlrev_b64 v[80:81], 11, v[68:69]
	v_add_u32_e32 v72, 0x90, v148
	v_lshl_add_u64 v[78:79], v[146:147], 0, v[80:81]
	v_ashrrev_i32_e32 v73, 31, v72
	v_lshlrev_b64 v[82:83], 11, v[72:73]
	v_lshl_add_u64 v[84:85], v[146:147], 0, v[82:83]
	global_store_dwordx4 v[76:77], v[64:67], off offset:256
	s_nop 0
	s_nop 0
	v_lshl_add_u64 v[80:81], s[92:93], 0, v[80:81]
	v_lshl_add_u64 v[80:81], v[80:81], 0, v[144:145]
	s_waitcnt vmcnt(15)
	v_lshlrev_b32_e32 v84, 16, v212
	v_and_b32_e32 v68, 0xffff0000, v212
	v_lshlrev_b32_e32 v85, 16, v213
	v_and_b32_e32 v69, 0xffff0000, v213
	v_lshlrev_b32_e32 v86, 16, v214
	v_and_b32_e32 v70, 0xffff0000, v214
	v_lshlrev_b32_e32 v87, 16, v215
	v_and_b32_e32 v71, 0xffff0000, v215
	v_fmac_f32_e32 v84, 0.5, v60
	v_fmac_f32_e32 v68, 0.5, v61
	v_fmac_f32_e32 v85, 0.5, v62
	v_fmac_f32_e32 v69, 0.5, v63
	s_waitcnt vmcnt(13)
	v_lshlrev_b32_e32 v60, 16, v220
	v_and_b32_e32 v61, 0xffff0000, v220
	v_lshlrev_b32_e32 v62, 16, v221
	v_and_b32_e32 v63, 0xffff0000, v221
	v_lshlrev_b32_e32 v64, 16, v222
	v_and_b32_e32 v65, 0xffff0000, v222
	v_fmac_f32_e32 v86, 0.5, v56
	v_fmac_f32_e32 v70, 0.5, v57
	v_fmac_f32_e32 v87, 0.5, v58
	v_fmac_f32_e32 v71, 0.5, v59
	v_cvt_pk_bf16_f32 v56, v84, v68
	v_cvt_pk_bf16_f32 v57, v85, v69
	v_cvt_pk_bf16_f32 v58, v86, v70
	v_cvt_pk_bf16_f32 v59, v87, v71
	v_lshlrev_b32_e32 v66, 16, v223
	v_and_b32_e32 v67, 0xffff0000, v223
	global_store_dwordx4 v[80:81], v[56:59], off
	v_fmac_f32_e32 v60, 0.5, v52
	v_fmac_f32_e32 v64, 0.5, v44
	v_fmac_f32_e32 v61, 0.5, v53
	v_fmac_f32_e32 v65, 0.5, v45
	v_fmac_f32_e32 v62, 0.5, v54
	v_fmac_f32_e32 v63, 0.5, v55
	v_cvt_pk_bf16_f32 v44, v60, v61
	v_cvt_pk_bf16_f32 v45, v62, v63
	v_fmac_f32_e32 v66, 0.5, v46
	v_fmac_f32_e32 v67, 0.5, v47
	v_cvt_pk_bf16_f32 v46, v64, v65
	v_cvt_pk_bf16_f32 v47, v66, v67
	global_store_dwordx4 v[80:81], v[44:47], off offset:256
	v_lshlrev_b32_e32 v88, 16, v216
	v_and_b32_e32 v52, 0xffff0000, v218
	v_and_b32_e32 v44, 0xffff0000, v216
	v_lshlrev_b32_e32 v45, 16, v217
	v_and_b32_e32 v46, 0xffff0000, v217
	v_lshlrev_b32_e32 v47, 16, v218
	v_fmac_f32_e32 v44, 0.5, v49
	v_fmac_f32_e32 v45, 0.5, v50
	v_fmac_f32_e32 v88, 0.5, v48
	v_fmac_f32_e32 v47, 0.5, v40
	v_fmac_f32_e32 v52, 0.5, v41
	v_fmac_f32_e32 v46, 0.5, v51
	v_cvt_pk_bf16_f32 v40, v88, v44
	v_cvt_pk_bf16_f32 v41, v45, v46
	v_lshl_add_u64 v[44:45], s[92:93], 0, v[82:83]
	v_lshlrev_b32_e32 v53, 16, v219
	v_and_b32_e32 v54, 0xffff0000, v219
	v_lshl_add_u64 v[44:45], v[44:45], 0, v[144:145]
	v_fmac_f32_e32 v53, 0.5, v42
	v_fmac_f32_e32 v54, 0.5, v43
	v_cvt_pk_bf16_f32 v42, v47, v52
	v_cvt_pk_bf16_f32 v43, v53, v54
	global_store_dwordx4 v[44:45], v[40:43], off
	s_waitcnt vmcnt(15)
;     __device__ __forceinline__ void operator()(const f32x4 (&acc)[2][2][4][2], const Unit& u, int wr, int wc, int fr, int fq) const {
;     ...
;                     const size_t off = (size_t)(u.pm * BM + ai * HALF + wr * 64 + (2 * mh + m2) * 16 + fr) * 1024 + col0 + bj * HALF;
;                     if (!basef) bh[m2][bj] = *(const u32x4*)(xin + off);
;                 }
; #pragma unroll
;             for (int m2 = 0; m2 < 2; ++m2) {
;                 const int m = 2 * mh + m2;
;                 const int row = u.pm * BM + ai * HALF + wr * 64 + m * 16 + fr; float sq = 0.f;
;                 if (basef) {
; #pragma unroll
;                     for (int bj = 0; bj < 2; ++bj) { const size_t off = (size_t)row * 1024 + col0 + bj * HALF; bf[m2][bj][0] = *(const f32x4*)(basef + off); bf[m2][bj][1] = *(const f32x4*)(basef + off + 4); }
;                 }
; #pragma unroll
;                 for (int bj = 0; bj < 2; ++bj) {
;                     const size_t off = (size_t)row * 1024 + col0 + bj * HALF;
;                     float bv[8];
;                     if (basef) { const f32x4 b0 = bf[m2][bj][0], b1 = bf[m2][bj][1]; bv[0] = b0[0]; bv[1] = b0[1]; bv[2] = b0[2]; bv[3] = b0[3]; bv[4] = b1[0]; bv[5] = b1[1]; bv[6] = b1[2]; bv[7] = b1[3]; }
;                     else { const u32x4 gw = bh[m2][bj];
;                         bv[0] = __uint_as_float(gw.x << 16); bv[1] = __uint_as_float(gw.x & 0xffff0000u); bv[2] = __uint_as_float(gw.y << 16); bv[3] = __uint_as_float(gw.y & 0xffff0000u);
;                         bv[4] = __uint_as_float(gw.z << 16); bv[5] = __uint_as_float(gw.z & 0xffff0000u); bv[6] = __uint_as_float(gw.w << 16); bv[7] = __uint_as_float(gw.w & 0xffff0000u); }
;                     float y[8];
; #pragma unroll
;                     for (int e = 0; e < 4; ++e) { y[e] = bv[e] + alpha * acc[ai][bj][m][0][e]; y[4 + e] = bv[4 + e] + alpha * acc[ai][bj][m][1][e]; }
;                     u32x4 w; w.x = cvt_pk_bf16(y[0], y[1]); w.y = cvt_pk_bf16(y[2], y[3]); w.z = cvt_pk_bf16(y[4], y[5]); w.w = cvt_pk_bf16(y[6], y[7]);
;                     *(u32x4*)(xs + off) = w;
;                     if (ss) sq += ((y[0] * y[0] + y[1] * y[1]) + (y[2] * y[2] + y[3] * y[3])) + ((y[4] * y[4] + y[5] * y[5]) + (y[6] * y[6] + y[7] * y[7]));
;                 }
	v_lshlrev_b32_e32 v48, 16, v227
	v_and_b32_e32 v49, 0xffff0000, v227
	v_lshlrev_b32_e32 v40, 16, v224
	v_and_b32_e32 v41, 0xffff0000, v224
	v_fmac_f32_e32 v40, 0.5, v36
	v_add_u32_e32 v36, 0xa0, v148
	v_lshlrev_b32_e32 v42, 16, v225
	v_and_b32_e32 v43, 0xffff0000, v225
	v_lshlrev_b32_e32 v46, 16, v226
	v_and_b32_e32 v47, 0xffff0000, v226
	v_fmac_f32_e32 v41, 0.5, v37
	v_fmac_f32_e32 v48, 0.5, v34
	v_fmac_f32_e32 v49, 0.5, v35
	v_ashrrev_i32_e32 v37, 31, v36
	v_fmac_f32_e32 v46, 0.5, v32
	v_fmac_f32_e32 v47, 0.5, v33
	v_fmac_f32_e32 v42, 0.5, v38
	v_fmac_f32_e32 v43, 0.5, v39
	v_cvt_pk_bf16_f32 v32, v40, v41
	v_cvt_pk_bf16_f32 v33, v42, v43
	v_cvt_pk_bf16_f32 v34, v46, v47
	v_cvt_pk_bf16_f32 v35, v48, v49
	v_lshlrev_b64 v[48:49], 11, v[36:37]
	v_lshl_add_u64 v[40:41], v[146:147], 0, v[48:49]
	global_store_dwordx4 v[44:45], v[32:35], off offset:256
	v_lshl_add_u64 v[48:49], s[92:93], 0, v[48:49]
	v_add_u32_e32 v40, 0xb0, v148
	v_ashrrev_i32_e32 v41, 31, v40
	v_lshlrev_b64 v[50:51], 11, v[40:41]
	v_lshl_add_u64 v[44:45], v[146:147], 0, v[50:51]
	s_nop 0
	v_lshl_add_u64 v[48:49], v[48:49], 0, v[144:145]
	s_waitcnt vmcnt(15)
	v_lshlrev_b32_e32 v52, 16, v228
	v_and_b32_e32 v36, 0xffff0000, v228
	v_lshlrev_b32_e32 v53, 16, v229
	v_and_b32_e32 v37, 0xffff0000, v229
	v_lshlrev_b32_e32 v54, 16, v230
	v_and_b32_e32 v38, 0xffff0000, v230
	v_lshlrev_b32_e32 v55, 16, v231
	v_and_b32_e32 v39, 0xffff0000, v231
	v_fmac_f32_e32 v52, 0.5, v28
	v_fmac_f32_e32 v54, 0.5, v24
	v_fmac_f32_e32 v36, 0.5, v29
	v_fmac_f32_e32 v38, 0.5, v25
	v_fmac_f32_e32 v53, 0.5, v30
	v_fmac_f32_e32 v37, 0.5, v31
	v_cvt_pk_bf16_f32 v24, v52, v36
	v_cvt_pk_bf16_f32 v25, v53, v37
	s_waitcnt vmcnt(14)
	v_lshlrev_b32_e32 v28, 16, v232
	v_and_b32_e32 v29, 0xffff0000, v232
	v_lshlrev_b32_e32 v30, 16, v233
	v_and_b32_e32 v31, 0xffff0000, v233
	v_lshlrev_b32_e32 v32, 16, v234
	v_and_b32_e32 v33, 0xffff0000, v234
	v_fmac_f32_e32 v55, 0.5, v26
	v_fmac_f32_e32 v39, 0.5, v27
	v_cvt_pk_bf16_f32 v26, v54, v38
	v_cvt_pk_bf16_f32 v27, v55, v39
	global_store_dwordx4 v[48:49], v[24:27], off
	v_fmac_f32_e32 v28, 0.5, v20
	v_fmac_f32_e32 v32, 0.5, v16
	v_lshlrev_b32_e32 v24, 16, v235
	v_and_b32_e32 v25, 0xffff0000, v235
	v_fmac_f32_e32 v29, 0.5, v21
	v_fmac_f32_e32 v33, 0.5, v17
	v_fmac_f32_e32 v30, 0.5, v22
	v_fmac_f32_e32 v31, 0.5, v23
	v_cvt_pk_bf16_f32 v16, v28, v29
	v_cvt_pk_bf16_f32 v17, v30, v31
	v_fmac_f32_e32 v24, 0.5, v18
	v_fmac_f32_e32 v25, 0.5, v19
	v_cvt_pk_bf16_f32 v18, v32, v33
	v_cvt_pk_bf16_f32 v19, v24, v25
	global_store_dwordx4 v[48:49], v[16:19], off offset:256
	s_waitcnt vmcnt(15)
	v_lshlrev_b32_e32 v20, 16, v238
	v_and_b32_e32 v21, 0xffff0000, v238
	v_lshlrev_b32_e32 v16, 16, v236
	v_and_b32_e32 v17, 0xffff0000, v236
	v_lshlrev_b32_e32 v18, 16, v237
	v_and_b32_e32 v19, 0xffff0000, v237
	v_lshlrev_b32_e32 v22, 16, v239
	v_and_b32_e32 v23, 0xffff0000, v239
	v_fmac_f32_e32 v16, 0.5, v12
	v_fmac_f32_e32 v17, 0.5, v13
	v_lshl_add_u64 v[12:13], s[92:93], 0, v[50:51]
	v_fmac_f32_e32 v20, 0.5, v8
	v_fmac_f32_e32 v21, 0.5, v9
	v_fmac_f32_e32 v18, 0.5, v14
	v_fmac_f32_e32 v22, 0.5, v10
	v_fmac_f32_e32 v19, 0.5, v15
	v_fmac_f32_e32 v23, 0.5, v11
	v_cvt_pk_bf16_f32 v8, v16, v17
	v_cvt_pk_bf16_f32 v9, v18, v19
	v_cvt_pk_bf16_f32 v10, v20, v21
	v_cvt_pk_bf16_f32 v11, v22, v23
	v_lshl_add_u64 v[12:13], v[12:13], 0, v[144:145]
	global_store_dwordx4 v[12:13], v[8:11], off
	s_waitcnt vmcnt(15)
	v_lshlrev_b32_e32 v14, 16, v242
	v_and_b32_e32 v15, 0xffff0000, v242
	v_lshlrev_b32_e32 v8, 16, v240
	v_and_b32_e32 v9, 0xffff0000, v240
	v_lshlrev_b32_e32 v10, 16, v241
	v_and_b32_e32 v11, 0xffff0000, v241
	v_lshlrev_b32_e32 v16, 16, v243
	v_and_b32_e32 v17, 0xffff0000, v243
	v_fmac_f32_e32 v8, 0.5, v4
	v_fmac_f32_e32 v14, 0.5, v0
	v_fmac_f32_e32 v9, 0.5, v5
	v_fmac_f32_e32 v15, 0.5, v1
	v_fmac_f32_e32 v10, 0.5, v6
	v_fmac_f32_e32 v16, 0.5, v2
	v_fmac_f32_e32 v11, 0.5, v7
	v_fmac_f32_e32 v17, 0.5, v3
	v_cvt_pk_bf16_f32 v0, v8, v9
	v_cvt_pk_bf16_f32 v1, v10, v11
	v_cvt_pk_bf16_f32 v2, v14, v15
	v_cvt_pk_bf16_f32 v3, v16, v17
	global_store_dwordx4 v[12:13], v[0:3], off offset:256
	s_cbranch_vccnz .LBB0_3256
	s_andn2_b64 vcc, exec, s[0:1]
	s_cbranch_vccnz .LBB0_3255
	s_barrier
	s_branch .LBB0_3255
